# v45 + attention step loops: dead m0 save/restore removed, loop-head 3-way wait test reduced to one compare, cmp pairs folded, rare blocks (reference raise, O rescale, band mask) moved out of line
# baseline (speedup 1.0000x reference)
.LBB0_764:
	s_mov_b64 s[8:9], s[0:1]
	v_mov_b32_e32 v36, v202
	s_load_dwordx2 s[92:93], s[8:9], 0xa0
	s_ashr_i32 s63, s62, 31
	v_readfirstlane_b32 s14, v36
	s_lshl_b32 s20, s60, 8
	s_lshl_b32 s6, s35, 7
	s_ashr_i32 s12, s14, 6
	s_lshl_b64 s[86:87], s[62:63], 13
	s_ashr_i32 s7, s20, 31
	s_add_u32 s10, s86, s20
	s_addc_u32 s37, s87, s7
	s_lshl_b32 s13, s12, 5
	s_ashr_i32 s24, s13, 31
	s_add_u32 s8, s10, s13
	s_addc_u32 s9, s37, s24
	s_ashr_i32 s7, s6, 31
	s_lshl_b64 s[80:81], s[8:9], 10
	s_lshl_b64 s[74:75], s[62:63], 24
	s_lshl_b64 s[64:65], s[6:7], 1
	s_waitcnt lgkmcnt(0)
	s_add_u32 s6, s92, s74
	s_addc_u32 s7, s93, s75
	v_and_b32_e32 v207, 63, v36
	s_add_u32 s6, s6, s64
	s_addc_u32 s7, s7, s65
	v_lshlrev_b32_e32 v2, 11, v207
	v_mov_b32_e32 v3, v146
	s_lshl_b32 s88, s12, 3
	v_lshl_add_u64 v[2:3], s[6:7], 0, v[2:3]
	s_ashr_i32 s89, s88, 31
	s_lshl_b32 s8, s12, 4
	v_bfe_u32 v37, v36, 2, 4
	v_lshl_add_u64 v[2:3], s[88:89], 1, v[2:3]
	v_and_or_b32 v211, s8, 48, v37
	v_lshl_add_u64 v[188:189], v[2:3], 0, s[16:17]
	v_lshlrev_b32_e32 v2, 11, v211
	v_mov_b32_e32 v3, v146
	v_lshl_add_u64 v[2:3], s[6:7], 0, v[2:3]
	s_ashr_i32 s6, s14, 3
	s_and_b32 s90, s6, 0xffffffe0
	s_ashr_i32 s91, s90, 31
	v_lshlrev_b32_e32 v210, 3, v36
	s_lshl_b32 s25, s12, 10
	v_and_b32_e32 v38, 24, v210
	s_cmp_lg_u32 0, -1
	v_and_b32_e32 v208, 31, v36
	v_lshl_add_u64 v[2:3], s[90:91], 1, v[2:3]
	v_lshlrev_b32_e32 v186, 1, v38
	v_mov_b32_e32 v187, v146
	s_cselect_b32 s6, 0, 0
	v_bfe_u32 v209, v36, 5, 1
	v_lshl_add_u64 v[2:3], v[2:3], 0, v[186:187]
	s_add_i32 s56, s25, s6
	v_lshlrev_b32_e32 v1, 11, v208
	v_lshl_add_u64 v[34:35], v[2:3], 0, s[58:59]
	s_add_i32 s55, s56, 0x6000
	s_add_i32 s54, s56, 0xe000
	s_andn2_b64 vcc, exec, s[4:5]
	v_lshl_or_b32 v184, v209, 4, v1
	s_cbranch_vccnz .LBB0_766
	s_lshl_b64 s[6:7], s[80:81], 1
	s_add_u32 s6, s92, s6
	s_addc_u32 s7, s93, s7
	s_add_u32 s6, s6, s64
	s_addc_u32 s7, s7, s65
	v_mov_b32_e32 v185, v146
	v_lshl_add_u64 v[2:3], s[6:7], 0, v[184:185]
	v_lshl_add_u64 v[4:5], v[2:3], 0, s[30:31]
	v_add_co_u32_e32 v2, vcc, s97, v2
	s_cmp_lg_u32 0, -1
	s_nop 0
	v_addc_co_u32_e32 v3, vcc, 0, v3, vcc
	global_load_dwordx4 v[152:155], v[4:5], off offset:32
	global_load_dwordx4 v[156:159], v[4:5], off offset:64
	global_load_dwordx4 v[148:151], v[2:3], off
	global_load_dwordx4 v[160:163], v[4:5], off offset:96
	s_mov_b32 m0, s56
	s_nop 0
	global_load_lds_dwordx4 v[188:189], off
	s_mov_b64 s[22:23], 0x20000
	s_mov_b32 m0, s55
	s_nop 0
	global_load_lds_dwordx4 v[34:35], off
	s_mov_b64 s[6:7], 0x80
	v_lshl_add_u64 v[2:3], v[34:35], 0, s[6:7]
	s_mov_b32 m0, s54
	s_nop 0
	global_load_lds_dwordx4 v[2:3], off
	s_cselect_b32 s6, 0, 0
	s_add_i32 s8, s6, s25
	v_lshl_add_u64 v[2:3], v[188:189], 0, s[22:23]
	s_add_i32 s6, s8, 0x2000
	s_mov_b32 m0, s6
	s_nop 0
	global_load_lds_dwordx4 v[2:3], off
	v_lshl_add_u64 v[2:3], v[34:35], 0, s[22:23]
	s_add_i32 s6, s8, 0x8000
	s_mov_b32 m0, s6
	s_nop 0
	global_load_lds_dwordx4 v[2:3], off
	s_mov_b64 s[6:7], 0x20080
	v_lshl_add_u64 v[2:3], v[34:35], 0, s[6:7]
	s_add_i32 s6, s8, 0x10000
	s_mov_b32 m0, s6
	s_nop 0
	global_load_lds_dwordx4 v[2:3], off
	s_mov_b64 s[6:7], 0x40000
	v_lshl_add_u64 v[2:3], v[188:189], 0, s[6:7]
	s_addk_i32 s8, 0x4000
	s_mov_b32 m0, s8
	s_nop 0
	global_load_lds_dwordx4 v[2:3], off

.LBB0_776:
	s_mov_b64 s[4:5], 0x40000
	s_cmp_lg_u32 0, -1
	v_lshl_add_u64 v[44:45], v[34:35], 0, s[4:5]
	s_cselect_b32 s4, 0, 0
	s_add_i32 s8, s4, s25
	s_add_i32 s4, s8, 0xa000
	s_mov_b32 m0, s4
	s_nop 0
	global_load_lds_dwordx4 v[44:45], off
	s_mov_b64 s[4:5], 0x40080
	v_lshl_add_u64 v[34:35], v[34:35], 0, s[4:5]
	s_add_i32 s8, s8, 0x12000
	s_mov_b32 m0, s8
	s_nop 0
	global_load_lds_dwordx4 v[34:35], off

.LBB0_781:
	s_cmp_lt_i32 s30, s71
	s_cselect_b64 s[4:5], -1, 0
	s_cselect_b64 s[96:97], 0, -1
	s_cbranch_scc0 .Lattn_head_rare_m0
	s_waitcnt vmcnt(3) lgkmcnt(0)
	s_barrier
.LBB0_785:
	s_add_i32 s22, s30, 1
	s_cmp_lt_i32 s22, s71
	s_cselect_b64 s[94:95], -1, 0
	s_cselect_b64 s[22:23], 0, -1
	v_lshl_add_u64 v[192:193], v[188:189], 0, s[92:93]
	s_cbranch_scc0 .LBB0_787
	s_mul_hi_u32 s28, s31, 0xaaaaaaab
	s_lshr_b32 s28, s28, 1
	s_mulk_i32 s28, 0x6000
	s_sub_i32 s28, s56, s28
	s_add_i32 s28, s14, s28
	v_lshl_add_u64 v[114:115], v[192:193], 0, s[38:39]
	s_addk_i32 s28, 0xa000
	s_mov_b32 m0, s28
	s_nop 0
	global_load_lds_dwordx4 v[114:115], off
.LBB0_787:
	s_andn2_b64 vcc, exec, s[4:5]
	v_lshl_add_u64 v[194:195], v[190:191], 0, s[92:93]
	s_cbranch_vccnz .LBB0_789
	s_add_i32 s4, s14, 0xffffe000
	s_and_b32 s4, s4, 0x6000
	s_add_i32 s5, s4, s54
	v_lshl_add_u64 v[114:115], v[194:195], 0, s[40:41]
	s_add_i32 s4, s4, s55
	s_mov_b32 m0, s4
	s_nop 0
	global_load_lds_dwordx4 v[114:115], off
	v_lshl_add_u64 v[116:117], v[194:195], 0, s[42:43]
	s_mov_b32 m0, s5
	s_nop 0
	global_load_lds_dwordx4 v[116:117], off
.LBB0_789:
	s_mul_hi_u32 s4, s61, 0xaaaaaaab
	s_lshr_b32 s50, s4, 1
	s_mul_i32 s4, s50, 0xffffa000
	s_add_i32 s4, s14, s4
	s_and_b32 s51, s14, 0x6000
	v_add_u32_e32 v217, s4, v214
	v_add_u32_e32 v216, s51, v147
	v_add_u32_e32 v217, 0xffffc000, v217
	ds_read_b64_tr_b16 v[118:119], v216 offset:24576
	ds_read_b64_tr_b16 v[120:121], v216 offset:25088
	ds_read_b64_tr_b16 v[122:123], v216 offset:28672
	ds_read_b64_tr_b16 v[124:125], v216 offset:29184
	ds_read_b128 v[114:117], v217
	s_waitcnt lgkmcnt(3)
	v_mfma_f32_32x32x16_bf16 v[18:33], v[164:167], v[118:121], v[18:33]
	ds_read_b64_tr_b16 v[126:127], v216 offset:57344
	ds_read_b64_tr_b16 v[128:129], v216 offset:57856
	s_waitcnt lgkmcnt(3)
	v_mfma_f32_32x32x16_bf16 v[50:65], v[164:167], v[122:125], v[50:65]
	ds_read_b64_tr_b16 v[130:131], v216 offset:61440
	ds_read_b64_tr_b16 v[132:133], v216 offset:61952
	s_waitcnt lgkmcnt(2)
	v_mfma_f32_32x32x16_bf16 v[34:49], v[164:167], v[126:129], v[34:49]
	ds_read_b64_tr_b16 v[118:119], v216 offset:25600
	ds_read_b64_tr_b16 v[120:121], v216 offset:26112
	s_waitcnt lgkmcnt(2)
	v_mfma_f32_32x32x16_bf16 v[2:17], v[164:167], v[130:133], v[2:17]
	ds_read_b64_tr_b16 v[180:181], v216 offset:29696
	ds_read_b64_tr_b16 v[182:183], v216 offset:30208
	v_max_f32_e32 v122, v98, v99
	v_max3_f32 v123, v100, v101, v67
	v_max3_f32 v122, v122, v66, v68
	v_max3_f32 v122, v122, v69, v102
	v_max3_f32 v123, v123, v104, v105
	v_max3_f32 v122, v122, v103, v70
	v_max3_f32 v123, v123, v72, v73
	v_max3_f32 v122, v122, v71, v106
	v_max3_f32 v123, v123, v108, v109
	v_max3_f32 v122, v122, v107, v74
	v_max3_f32 v123, v123, v76, v77
	v_max3_f32 v122, v122, v75, v110
	v_max3_f32 v123, v123, v112, v113
	v_max3_f32 v122, v122, v111, v78
	v_max3_f32 v123, v123, v80, v81
	v_max3_f32 v122, v122, v79, v123
	v_mov_b32_e32 v123, v122
	s_nop 1
	v_permlane32_swap_b32_e32 v122, v123
	v_max_f32_e32 v122, v122, v123
	v_cmp_lt_f32_e32 vcc, s15, v122
	s_cmp_lg_u64 vcc, 0
	s_cselect_b64 s[4:5], -1, 0
	s_cbranch_vccnz .Lattn_rare_m0_a1
.LBB0_793:
	v_exp_f32_e32 v164, v98
	v_mfma_f32_32x32x16_bf16 v[130:145], v[114:117], v[148:151], v[82:97]
	v_exp_f32_e32 v165, v99
	v_exp_f32_e32 v230, v100
	ds_read_b64_tr_b16 v[218:219], v216 offset:58368
	ds_read_b64_tr_b16 v[220:221], v216 offset:58880
	v_exp_f32_e32 v231, v101
	ds_read_b128 v[222:225], v217 offset:512
	s_waitcnt lgkmcnt(5)
	v_mfma_f32_32x32x16_bf16 v[18:33], v[168:171], v[118:121], v[18:33]
	v_add_f32_e32 v98, v165, v164
	v_add_f32_e32 v98, v230, v98
	v_add_f32_e32 v232, v231, v98
	ds_read_b64_tr_b16 v[98:99], v216 offset:62464
	ds_read_b64_tr_b16 v[100:101], v216 offset:62976
	ds_read_b128 v[226:229], v217 offset:2048
	v_exp_f32_e32 v233, v102
	s_waitcnt lgkmcnt(3)
	v_mfma_f32_32x32x16_bf16 v[114:129], v[222:225], v[148:151], v[82:97]
	v_exp_f32_e32 v222, v103
	v_exp_f32_e32 v223, v104
	v_exp_f32_e32 v224, v105
	v_add_f32_e32 v102, v233, v232
	v_add_f32_e32 v102, v222, v102
	v_add_f32_e32 v102, v223, v102
	v_add_f32_e32 v225, v224, v102
	v_mfma_f32_32x32x16_bf16 v[50:65], v[168:171], v[180:183], v[50:65]
	v_exp_f32_e32 v232, v106
	s_waitcnt lgkmcnt(0)
	v_mfma_f32_32x32x16_bf16 v[130:145], v[226:229], v[152:155], v[130:145]
	v_exp_f32_e32 v234, v107
	v_exp_f32_e32 v226, v108
	ds_read_b64_tr_b16 v[102:103], v216 offset:26624
	ds_read_b64_tr_b16 v[104:105], v216 offset:27136
	v_exp_f32_e32 v227, v109
	ds_read_b128 v[180:183], v217 offset:2560
	v_add_f32_e32 v106, v232, v225
	v_mfma_f32_32x32x16_bf16 v[34:49], v[168:171], v[218:221], v[34:49]
	v_add_f32_e32 v106, v234, v106
	v_add_f32_e32 v106, v226, v106
	v_add_f32_e32 v225, v227, v106
	v_cvt_pk_bf16_f32 v164, v164, v165
	v_cvt_pk_bf16_f32 v165, v230, v231
	v_exp_f32_e32 v228, v110
	s_waitcnt lgkmcnt(0)
	v_mfma_f32_32x32x16_bf16 v[114:129], v[180:183], v[152:155], v[114:129]
	v_exp_f32_e32 v229, v111
	v_exp_f32_e32 v180, v112
	ds_read_b64_tr_b16 v[106:107], v216 offset:30720
	ds_read_b64_tr_b16 v[108:109], v216 offset:31232
	v_exp_f32_e32 v181, v113
	ds_read_b128 v[218:221], v217 offset:4096
	v_add_f32_e32 v110, v228, v225
	v_mfma_f32_32x32x16_bf16 v[2:17], v[168:171], v[98:101], v[2:17]
	v_add_f32_e32 v110, v229, v110
	v_add_f32_e32 v110, v180, v110
	v_add_f32_e32 v182, v181, v110
	v_cvt_pk_bf16_f32 v166, v233, v222
	v_cvt_pk_bf16_f32 v167, v223, v224
	s_waitcnt lgkmcnt(0)
	v_mfma_f32_32x32x16_bf16 v[130:145], v[218:221], v[156:159], v[130:145]
	v_exp_f32_e32 v183, v66
	ds_read_b64_tr_b16 v[98:99], v216 offset:59392
	ds_read_b64_tr_b16 v[100:101], v216 offset:59904
	v_exp_f32_e32 v222, v67
	ds_read_b128 v[110:113], v217 offset:4608
	v_add_f32_e32 v66, v183, v182
	v_cvt_pk_bf16_f32 v168, v232, v234
	v_mfma_f32_32x32x16_bf16 v[18:33], v[172:175], v[102:105], v[18:33]
	v_add_f32_e32 v66, v222, v66
	v_cvt_pk_bf16_f32 v169, v226, v227
	v_mfma_f32_32x32x16_bf16 v[50:65], v[172:175], v[106:109], v[50:65]
	v_exp_f32_e32 v182, v68
	ds_read_b64_tr_b16 v[102:103], v216 offset:63488
	ds_read_b64_tr_b16 v[104:105], v216 offset:64000
	v_exp_f32_e32 v218, v69
	v_cvt_pk_bf16_f32 v170, v228, v229
	v_add_f32_e32 v66, v182, v66
	v_cvt_pk_bf16_f32 v171, v180, v181
	v_add_f32_e32 v219, v218, v66
	s_waitcnt lgkmcnt(2)
	v_mfma_f32_32x32x16_bf16 v[114:129], v[110:113], v[156:159], v[114:129]
	v_exp_f32_e32 v110, v70
	ds_read_b64_tr_b16 v[66:67], v216 offset:27648
	ds_read_b64_tr_b16 v[68:69], v216 offset:28160
	v_exp_f32_e32 v111, v71
	ds_read_b128 v[106:109], v217 offset:6144
	v_add_f32_e32 v70, v110, v219
	v_add_f32_e32 v70, v111, v70
	v_mfma_f32_32x32x16_bf16 v[34:49], v[172:175], v[98:101], v[34:49]
	s_waitcnt lgkmcnt(3)
	v_mfma_f32_32x32x16_bf16 v[2:17], v[172:175], v[102:105], v[2:17]
	v_exp_f32_e32 v112, v72
	ds_read_b64_tr_b16 v[98:99], v216 offset:31744
	ds_read_b64_tr_b16 v[100:101], v216 offset:32256
	v_exp_f32_e32 v113, v73
	v_add_f32_e32 v70, v112, v70
	v_add_f32_e32 v172, v113, v70
	s_waitcnt lgkmcnt(2)
	v_mfma_f32_32x32x16_bf16 v[130:145], v[106:109], v[160:163], v[130:145]
	v_exp_f32_e32 v74, v74
	ds_read_b64_tr_b16 v[70:71], v216 offset:60416
	ds_read_b64_tr_b16 v[72:73], v216 offset:60928
	v_exp_f32_e32 v75, v75
	ds_read_b128 v[102:105], v217 offset:6656
	v_add_f32_e32 v106, v74, v172
	v_cvt_pk_bf16_f32 v172, v183, v222
	v_mfma_f32_32x32x16_bf16 v[18:33], v[176:179], v[66:69], v[18:33]
	v_add_f32_e32 v106, v75, v106
	v_cvt_pk_bf16_f32 v173, v182, v218
	s_waitcnt lgkmcnt(3)
	v_mfma_f32_32x32x16_bf16 v[50:65], v[176:179], v[98:101], v[50:65]
	v_exp_f32_e32 v76, v76
	v_exp_f32_e32 v77, v77
	ds_read_b64_tr_b16 v[66:67], v216 offset:64512
	ds_read_b64_tr_b16 v[68:69], v216 offset:65024
	v_cvt_pk_bf16_f32 v174, v110, v111
	v_add_f32_e32 v106, v76, v106
	v_add_f32_e32 v106, v77, v106
	v_cvt_pk_bf16_f32 v175, v112, v113
	s_waitcnt lgkmcnt(2)
	v_mfma_f32_32x32x16_bf16 v[114:129], v[102:105], v[160:163], v[114:129]
	v_exp_f32_e32 v78, v78
	v_exp_f32_e32 v79, v79
	v_add_f32_e32 v98, v78, v106
	v_add_f32_e32 v98, v79, v98
	v_mfma_f32_32x32x16_bf16 v[34:49], v[176:179], v[70:73], v[34:49]
	s_waitcnt lgkmcnt(0)
	v_mfma_f32_32x32x16_bf16 v[2:17], v[176:179], v[66:69], v[2:17]
	v_exp_f32_e32 v80, v80
	v_exp_f32_e32 v81, v81
	v_add_f32_e32 v66, v80, v98
	v_add_f32_e32 v66, v81, v66
	s_andn2_b64 vcc, exec, s[4:5]
	s_cbranch_vccz .Lattn_rare_m0_b2
.LBB0_795:
	s_add_i32 s28, s33, s30
	s_add_i32 s4, s28, 3
	s_cmp_lt_i32 s4, 0
	s_cbranch_scc0 .Lattn_rare_m0_c3

.LBB0_801:
	v_lshl_add_u64 v[68:69], v[194:195], 0, s[46:47]
	s_add_i32 s5, s51, s55
	s_mov_b32 m0, s5
	s_nop 0
	global_load_lds_dwordx4 v[68:69], off
	s_add_i32 s4, s51, s54
	v_lshl_add_u64 v[70:71], v[194:195], 0, s[48:49]
	s_mov_b32 m0, s4
	s_nop 0
	global_load_lds_dwordx4 v[70:71], off
.LBB0_802:
	s_mul_hi_u32 s4, s30, 0xaaaaaaab
	s_lshr_b32 s4, s4, 1
	s_mulk_i32 s4, 0xa000
	s_add_i32 s5, s14, 0xffffa000
	s_add_i32 s4, s14, s4
	s_and_b32 s5, s5, 0x6000
	v_add_u32_e32 v194, s4, v214
	v_add_f32_e32 v192, v213, v66
	v_add_u32_e32 v193, s5, v147
	v_add_u32_e32 v194, 0xffffe000, v194
	ds_read_b64_tr_b16 v[70:71], v193 offset:24576
	ds_read_b64_tr_b16 v[72:73], v193 offset:25088
	ds_read_b64_tr_b16 v[98:99], v193 offset:28672
	ds_read_b64_tr_b16 v[100:101], v193 offset:29184
	ds_read_b128 v[66:69], v194
	s_waitcnt lgkmcnt(3)
	v_mfma_f32_32x32x16_bf16 v[18:33], v[164:167], v[70:73], v[18:33]
	ds_read_b64_tr_b16 v[102:103], v193 offset:57344
	ds_read_b64_tr_b16 v[104:105], v193 offset:57856
	s_waitcnt lgkmcnt(3)
	v_mfma_f32_32x32x16_bf16 v[50:65], v[164:167], v[98:101], v[50:65]
	ds_read_b64_tr_b16 v[106:107], v193 offset:61440
	ds_read_b64_tr_b16 v[108:109], v193 offset:61952
	s_waitcnt lgkmcnt(2)
	v_mfma_f32_32x32x16_bf16 v[34:49], v[164:167], v[102:105], v[34:49]
	ds_read_b64_tr_b16 v[70:71], v193 offset:25600
	ds_read_b64_tr_b16 v[72:73], v193 offset:26112
	s_waitcnt lgkmcnt(2)
	v_mfma_f32_32x32x16_bf16 v[2:17], v[164:167], v[106:109], v[2:17]
	ds_read_b64_tr_b16 v[180:181], v193 offset:29696
	ds_read_b64_tr_b16 v[182:183], v193 offset:30208
	v_max_f32_e32 v98, v130, v131
	v_max3_f32 v99, v132, v133, v115
	v_max3_f32 v98, v98, v114, v116
	v_max3_f32 v98, v98, v117, v134
	v_max3_f32 v99, v99, v136, v137
	v_max3_f32 v98, v98, v135, v118
	v_max3_f32 v99, v99, v120, v121
	v_max3_f32 v98, v98, v119, v138
	v_max3_f32 v99, v99, v140, v141
	v_max3_f32 v98, v98, v139, v122
	v_max3_f32 v99, v99, v124, v125
	v_max3_f32 v98, v98, v123, v142
	v_max3_f32 v99, v99, v144, v145
	v_max3_f32 v98, v98, v143, v126
	v_max3_f32 v99, v99, v128, v129
	v_max3_f32 v98, v98, v127, v99
	v_mov_b32_e32 v99, v98
	s_nop 1
	v_permlane32_swap_b32_e32 v98, v99
	v_max_f32_e32 v98, v98, v99
	v_cmp_lt_f32_e32 vcc, s15, v98
	s_cmp_lg_u64 vcc, 0
	s_cselect_b64 s[4:5], -1, 0
	s_cbranch_vccnz .Lattn_rare_m0_a4
.LBB0_806:
	v_cvt_pk_bf16_f32 v176, v74, v75
	v_cvt_pk_bf16_f32 v177, v76, v77
	v_cvt_pk_bf16_f32 v178, v78, v79
	v_cvt_pk_bf16_f32 v179, v80, v81
	v_exp_f32_e32 v164, v130
	v_mfma_f32_32x32x16_bf16 v[98:113], v[66:69], v[148:151], v[82:97]
	v_exp_f32_e32 v165, v131
	v_exp_f32_e32 v195, v132
	ds_read_b64_tr_b16 v[216:217], v193 offset:58368
	ds_read_b64_tr_b16 v[218:219], v193 offset:58880
	v_exp_f32_e32 v213, v133
	ds_read_b128 v[220:223], v194 offset:512
	s_waitcnt lgkmcnt(5)
	v_mfma_f32_32x32x16_bf16 v[18:33], v[168:171], v[70:73], v[18:33]
	v_add_f32_e32 v66, v165, v164
	v_add_f32_e32 v66, v195, v66
	v_add_f32_e32 v228, v213, v66
	ds_read_b64_tr_b16 v[130:131], v193 offset:62464
	ds_read_b64_tr_b16 v[132:133], v193 offset:62976
	ds_read_b128 v[224:227], v194 offset:2048
	v_exp_f32_e32 v229, v134
	s_waitcnt lgkmcnt(3)
	v_mfma_f32_32x32x16_bf16 v[66:81], v[220:223], v[148:151], v[82:97]
	v_exp_f32_e32 v220, v135
	v_exp_f32_e32 v221, v136
	v_exp_f32_e32 v222, v137
	v_add_f32_e32 v134, v229, v228
	v_add_f32_e32 v134, v220, v134
	v_add_f32_e32 v134, v221, v134
	v_add_f32_e32 v223, v222, v134
	v_mfma_f32_32x32x16_bf16 v[50:65], v[168:171], v[180:183], v[50:65]
	v_exp_f32_e32 v228, v138
	s_waitcnt lgkmcnt(0)
	v_mfma_f32_32x32x16_bf16 v[98:113], v[224:227], v[152:155], v[98:113]
	v_exp_f32_e32 v230, v139
	v_exp_f32_e32 v224, v140
	ds_read_b64_tr_b16 v[134:135], v193 offset:26624
	ds_read_b64_tr_b16 v[136:137], v193 offset:27136
	v_exp_f32_e32 v225, v141
	ds_read_b128 v[180:183], v194 offset:2560
	v_add_f32_e32 v138, v228, v223
	v_mfma_f32_32x32x16_bf16 v[34:49], v[168:171], v[216:219], v[34:49]
	v_add_f32_e32 v138, v230, v138
	v_add_f32_e32 v138, v224, v138
	v_add_f32_e32 v223, v225, v138
	v_cvt_pk_bf16_f32 v164, v164, v165
	v_cvt_pk_bf16_f32 v165, v195, v213
	v_exp_f32_e32 v195, v142
	s_waitcnt lgkmcnt(0)
	v_mfma_f32_32x32x16_bf16 v[66:81], v[180:183], v[152:155], v[66:81]
	v_exp_f32_e32 v213, v143
	v_exp_f32_e32 v180, v144
	ds_read_b64_tr_b16 v[138:139], v193 offset:30720
	ds_read_b64_tr_b16 v[140:141], v193 offset:31232
	v_exp_f32_e32 v181, v145
	ds_read_b128 v[216:219], v194 offset:4096
	v_add_f32_e32 v142, v195, v223
	v_mfma_f32_32x32x16_bf16 v[2:17], v[168:171], v[130:133], v[2:17]
	v_add_f32_e32 v142, v213, v142
	v_add_f32_e32 v142, v180, v142
	v_add_f32_e32 v182, v181, v142
	v_cvt_pk_bf16_f32 v166, v229, v220
	v_cvt_pk_bf16_f32 v167, v221, v222
	s_waitcnt lgkmcnt(0)
	v_mfma_f32_32x32x16_bf16 v[98:113], v[216:219], v[156:159], v[98:113]
	v_exp_f32_e32 v183, v114
	ds_read_b64_tr_b16 v[130:131], v193 offset:59392
	ds_read_b64_tr_b16 v[132:133], v193 offset:59904
	v_exp_f32_e32 v220, v115
	ds_read_b128 v[142:145], v194 offset:4608
	v_add_f32_e32 v114, v183, v182
	v_cvt_pk_bf16_f32 v168, v228, v230
	v_mfma_f32_32x32x16_bf16 v[18:33], v[172:175], v[134:137], v[18:33]
	v_add_f32_e32 v114, v220, v114
	v_cvt_pk_bf16_f32 v169, v224, v225
	v_mfma_f32_32x32x16_bf16 v[50:65], v[172:175], v[138:141], v[50:65]
	v_exp_f32_e32 v182, v116
	ds_read_b64_tr_b16 v[134:135], v193 offset:63488
	ds_read_b64_tr_b16 v[136:137], v193 offset:64000
	v_exp_f32_e32 v216, v117
	v_cvt_pk_bf16_f32 v170, v195, v213
	v_add_f32_e32 v114, v182, v114
	v_cvt_pk_bf16_f32 v171, v180, v181
	v_add_f32_e32 v114, v216, v114
	s_waitcnt lgkmcnt(2)
	v_mfma_f32_32x32x16_bf16 v[66:81], v[142:145], v[156:159], v[66:81]
	v_exp_f32_e32 v142, v118
	ds_read_b64_tr_b16 v[138:139], v193 offset:27648
	ds_read_b64_tr_b16 v[140:141], v193 offset:28160
	v_exp_f32_e32 v143, v119
	ds_read_b128 v[116:119], v194 offset:6144
	v_add_f32_e32 v114, v142, v114
	v_add_f32_e32 v114, v143, v114
	v_mfma_f32_32x32x16_bf16 v[34:49], v[172:175], v[130:133], v[34:49]
	s_waitcnt lgkmcnt(3)
	v_mfma_f32_32x32x16_bf16 v[2:17], v[172:175], v[134:137], v[2:17]
	v_exp_f32_e32 v144, v120
	ds_read_b64_tr_b16 v[130:131], v193 offset:31744
	ds_read_b64_tr_b16 v[132:133], v193 offset:32256
	v_exp_f32_e32 v145, v121
	v_add_f32_e32 v114, v144, v114
	v_add_f32_e32 v172, v145, v114
	s_waitcnt lgkmcnt(2)
	v_mfma_f32_32x32x16_bf16 v[98:113], v[116:119], v[160:163], v[98:113]
	v_exp_f32_e32 v114, v122
	ds_read_b64_tr_b16 v[134:135], v193 offset:60416
	ds_read_b64_tr_b16 v[136:137], v193 offset:60928
	v_exp_f32_e32 v115, v123
	ds_read_b128 v[118:121], v194 offset:6656
	v_add_f32_e32 v116, v114, v172
	v_cvt_pk_bf16_f32 v172, v183, v220
	v_mfma_f32_32x32x16_bf16 v[18:33], v[176:179], v[138:141], v[18:33]
	v_add_f32_e32 v180, v115, v116
	v_cvt_pk_bf16_f32 v173, v182, v216
	s_waitcnt lgkmcnt(3)
	v_mfma_f32_32x32x16_bf16 v[50:65], v[176:179], v[130:133], v[50:65]
	v_exp_f32_e32 v116, v124
	v_exp_f32_e32 v117, v125
	ds_read_b64_tr_b16 v[122:123], v193 offset:64512
	ds_read_b64_tr_b16 v[124:125], v193 offset:65024
	v_cvt_pk_bf16_f32 v174, v142, v143
	v_add_f32_e32 v138, v116, v180
	v_add_f32_e32 v138, v117, v138
	v_cvt_pk_bf16_f32 v175, v144, v145
	s_waitcnt lgkmcnt(2)
	v_mfma_f32_32x32x16_bf16 v[66:81], v[118:121], v[160:163], v[66:81]
	v_exp_f32_e32 v118, v126
	v_exp_f32_e32 v119, v127
	v_add_f32_e32 v120, v118, v138
	v_add_f32_e32 v126, v119, v120
	v_mfma_f32_32x32x16_bf16 v[34:49], v[176:179], v[134:137], v[34:49]
	s_waitcnt lgkmcnt(0)
	v_mfma_f32_32x32x16_bf16 v[2:17], v[176:179], v[122:125], v[2:17]
	v_exp_f32_e32 v120, v128
	v_exp_f32_e32 v121, v129
	v_add_f32_e32 v122, v120, v126
	v_add_f32_e32 v122, v121, v122
	s_andn2_b64 vcc, exec, s[4:5]
	s_cbranch_vccz .Lattn_rare_m0_b5
.LBB0_808:
	s_add_i32 s28, s28, 4
	s_cmp_lt_i32 s28, 0
	s_cbranch_scc0 .Lattn_rare_m0_c6

.Lattn_head_rare_m0:
	s_waitcnt vmcnt(2) lgkmcnt(0)
	s_barrier
	s_branch .LBB0_785
.Lattn_rare_m0_a1:
	v_max_f32_e32 v82, v122, v122
	v_max_f32_e32 v122, 0, v82
	v_exp_f32_e64 v123, -v122
	v_add_f32_e32 v212, v212, v122
	v_xor_b32_e32 v82, 0x80000000, v212
	v_mov_b32_e32 v83, v82
	v_mov_b32_e32 v84, v82
	v_mov_b32_e32 v85, v82
	v_mov_b32_e32 v86, v82
	v_mov_b32_e32 v87, v82
	v_mov_b32_e32 v88, v82
	v_mov_b32_e32 v89, v82
	v_mov_b32_e32 v90, v82
	v_mov_b32_e32 v91, v82
	v_mov_b32_e32 v92, v82
	v_mov_b32_e32 v93, v82
	v_mov_b32_e32 v94, v82
	v_mov_b32_e32 v95, v82
	v_mov_b32_e32 v96, v82
	v_mov_b32_e32 v97, v82
	s_and_saveexec_b64 vcc, s[8:9]
	ds_write_b32 v1, v123
	s_or_b64 exec, exec, vcc
	v_sub_f32_e32 v113, v113, v122
	v_sub_f32_e32 v112, v112, v122
	v_sub_f32_e32 v111, v111, v122
	v_sub_f32_e32 v110, v110, v122
	v_sub_f32_e32 v109, v109, v122
	v_sub_f32_e32 v108, v108, v122
	v_sub_f32_e32 v107, v107, v122
	v_sub_f32_e32 v106, v106, v122
	v_sub_f32_e32 v105, v105, v122
	v_sub_f32_e32 v104, v104, v122
	v_sub_f32_e32 v103, v103, v122
	v_sub_f32_e32 v102, v102, v122
	v_sub_f32_e32 v101, v101, v122
	v_sub_f32_e32 v100, v100, v122
	v_sub_f32_e32 v99, v99, v122
	v_sub_f32_e32 v98, v98, v122
	v_sub_f32_e32 v81, v81, v122
	v_sub_f32_e32 v80, v80, v122
	v_sub_f32_e32 v79, v79, v122
	v_sub_f32_e32 v78, v78, v122
	v_sub_f32_e32 v77, v77, v122
	v_sub_f32_e32 v76, v76, v122
	v_sub_f32_e32 v75, v75, v122
	v_sub_f32_e32 v74, v74, v122
	v_sub_f32_e32 v73, v73, v122
	v_sub_f32_e32 v72, v72, v122
	v_sub_f32_e32 v71, v71, v122
	v_sub_f32_e32 v70, v70, v122
	v_sub_f32_e32 v69, v69, v122
	v_sub_f32_e32 v68, v68, v122
	v_sub_f32_e32 v67, v67, v122
	v_sub_f32_e32 v66, v66, v122
	v_mul_f32_e32 v213, v213, v123
	s_branch .LBB0_793
.Lattn_rare_m0_b2:
	s_waitcnt lgkmcnt(0)
	ds_read_b128 v[68:71], v215 offset:96
	ds_read_b128 v[98:101], v215 offset:64
	ds_read_b128 v[102:105], v215 offset:32
	ds_read_b128 v[106:109], v215
	s_waitcnt lgkmcnt(0)
	s_waitcnt lgkmcnt(3)
	v_pk_mul_f32 v[30:31], v[30:31], v[68:69]
	s_waitcnt lgkmcnt(2)
	v_pk_mul_f32 v[26:27], v[26:27], v[98:99]
	s_waitcnt lgkmcnt(1)
	v_pk_mul_f32 v[22:23], v[22:23], v[102:103]
	v_pk_mul_f32 v[32:33], v[32:33], v[70:71]
	v_pk_mul_f32 v[28:29], v[28:29], v[100:101]
	v_pk_mul_f32 v[24:25], v[24:25], v[104:105]
	s_waitcnt lgkmcnt(0)
	v_pk_mul_f32 v[20:21], v[20:21], v[108:109]
	v_pk_mul_f32 v[18:19], v[18:19], v[106:107]
	v_pk_mul_f32 v[62:63], v[62:63], v[68:69]
	v_pk_mul_f32 v[58:59], v[58:59], v[98:99]
	v_pk_mul_f32 v[54:55], v[54:55], v[102:103]
	v_pk_mul_f32 v[64:65], v[64:65], v[70:71]
	v_pk_mul_f32 v[60:61], v[60:61], v[100:101]
	v_pk_mul_f32 v[56:57], v[56:57], v[104:105]
	v_pk_mul_f32 v[52:53], v[52:53], v[108:109]
	v_pk_mul_f32 v[50:51], v[50:51], v[106:107]
	v_pk_mul_f32 v[46:47], v[46:47], v[68:69]
	v_pk_mul_f32 v[42:43], v[42:43], v[98:99]
	v_pk_mul_f32 v[38:39], v[38:39], v[102:103]
	v_pk_mul_f32 v[48:49], v[48:49], v[70:71]
	v_pk_mul_f32 v[44:45], v[44:45], v[100:101]
	v_pk_mul_f32 v[40:41], v[40:41], v[104:105]
	v_pk_mul_f32 v[36:37], v[36:37], v[108:109]
	v_pk_mul_f32 v[34:35], v[34:35], v[106:107]
	v_pk_mul_f32 v[14:15], v[14:15], v[68:69]
	v_pk_mul_f32 v[10:11], v[10:11], v[98:99]
	v_pk_mul_f32 v[6:7], v[6:7], v[102:103]
	v_pk_mul_f32 v[16:17], v[16:17], v[70:71]
	v_pk_mul_f32 v[12:13], v[12:13], v[100:101]
	v_pk_mul_f32 v[8:9], v[8:9], v[104:105]
	v_pk_mul_f32 v[4:5], v[4:5], v[108:109]
	v_pk_mul_f32 v[2:3], v[2:3], v[106:107]
	s_branch .LBB0_795
.Lattn_rare_m0_c3:
	v_add_u32_e32 v67, 32, v187
	v_cmp_le_i32_e32 vcc, v67, v185
	v_add_u32_e32 v67, 33, v187
	s_nop 0
	v_cndmask_b32_e32 v114, v206, v114, vcc
	v_cmp_lt_i32_e32 vcc, v187, v185
	s_nop 1
	v_cndmask_b32_e32 v131, v206, v131, vcc
	v_cmp_le_i32_e32 vcc, v187, v185
	s_nop 1
	v_cndmask_b32_e32 v130, v206, v130, vcc
	v_cmp_le_i32_e32 vcc, v67, v185
	v_add_u32_e32 v67, 2, v187
	s_nop 0
	v_cndmask_b32_e32 v115, v206, v115, vcc
	v_cmp_le_i32_e32 vcc, v67, v185
	v_add_u32_e32 v67, 34, v187
	s_nop 0
	v_cndmask_b32_e32 v132, v206, v132, vcc
	v_cmp_le_i32_e32 vcc, v67, v185
	v_add_u32_e32 v67, 3, v187
	s_nop 0
	v_cndmask_b32_e32 v116, v206, v116, vcc
	v_cmp_le_i32_e32 vcc, v67, v185
	v_add_u32_e32 v67, 35, v187
	s_nop 0
	v_cndmask_b32_e32 v133, v206, v133, vcc
	v_cmp_le_i32_e32 vcc, v67, v185
	v_add_u32_e32 v67, 8, v187
	s_nop 0
	v_cndmask_b32_e32 v117, v206, v117, vcc
	v_cmp_le_i32_e32 vcc, v67, v185
	v_add_u32_e32 v67, 40, v187
	s_nop 0
	v_cndmask_b32_e32 v134, v206, v134, vcc
	v_cmp_le_i32_e32 vcc, v67, v185
	v_add_u32_e32 v67, 9, v187
	s_nop 0
	v_cndmask_b32_e32 v118, v206, v118, vcc
	v_cmp_le_i32_e32 vcc, v67, v185
	v_add_u32_e32 v67, 41, v187
	s_nop 0
	v_cndmask_b32_e32 v135, v206, v135, vcc
	v_cmp_le_i32_e32 vcc, v67, v185
	v_add_u32_e32 v67, 10, v187
	s_nop 0
	v_cndmask_b32_e32 v119, v206, v119, vcc
	v_cmp_le_i32_e32 vcc, v67, v185
	v_add_u32_e32 v67, 42, v187
	s_nop 0
	v_cndmask_b32_e32 v136, v206, v136, vcc
	v_cmp_le_i32_e32 vcc, v67, v185
	v_add_u32_e32 v67, 11, v187
	s_nop 0
	v_cndmask_b32_e32 v120, v206, v120, vcc
	v_cmp_le_i32_e32 vcc, v67, v185
	v_add_u32_e32 v67, 43, v187
	s_nop 0
	v_cndmask_b32_e32 v137, v206, v137, vcc
	v_cmp_le_i32_e32 vcc, v67, v185
	v_add_u32_e32 v67, 16, v187
	s_nop 0
	v_cndmask_b32_e32 v121, v206, v121, vcc
	v_cmp_le_i32_e32 vcc, v67, v185
	v_add_u32_e32 v67, 48, v187
	s_nop 0
	v_cndmask_b32_e32 v138, v206, v138, vcc
	v_cmp_le_i32_e32 vcc, v67, v185
	v_add_u32_e32 v67, 17, v187
	s_nop 0
	v_cndmask_b32_e32 v122, v206, v122, vcc
	v_cmp_le_i32_e32 vcc, v67, v185
	v_add_u32_e32 v67, 49, v187
	s_nop 0
	v_cndmask_b32_e32 v139, v206, v139, vcc
	v_cmp_le_i32_e32 vcc, v67, v185
	v_add_u32_e32 v67, 18, v187
	s_nop 0
	v_cndmask_b32_e32 v123, v206, v123, vcc
	v_cmp_le_i32_e32 vcc, v67, v185
	v_add_u32_e32 v67, 50, v187
	s_nop 0
	v_cndmask_b32_e32 v140, v206, v140, vcc
	v_cmp_le_i32_e32 vcc, v67, v185
	v_add_u32_e32 v67, 19, v187
	s_nop 0
	v_cndmask_b32_e32 v124, v206, v124, vcc
	v_cmp_le_i32_e32 vcc, v67, v185
	v_add_u32_e32 v67, 51, v187
	s_nop 0
	v_cndmask_b32_e32 v141, v206, v141, vcc
	v_cmp_le_i32_e32 vcc, v67, v185
	v_add_u32_e32 v67, 24, v187
	s_nop 0
	v_cndmask_b32_e32 v125, v206, v125, vcc
	v_cmp_le_i32_e32 vcc, v67, v185
	v_add_u32_e32 v67, 56, v187
	s_nop 0
	v_cndmask_b32_e32 v142, v206, v142, vcc
	v_cmp_le_i32_e32 vcc, v67, v185
	v_add_u32_e32 v67, 25, v187
	s_nop 0
	v_cndmask_b32_e32 v126, v206, v126, vcc
	v_cmp_le_i32_e32 vcc, v67, v185
	v_add_u32_e32 v67, 57, v187
	s_nop 0
	v_cndmask_b32_e32 v143, v206, v143, vcc
	v_cmp_le_i32_e32 vcc, v67, v185
	v_add_u32_e32 v67, 26, v187
	s_nop 0
	v_cndmask_b32_e32 v127, v206, v127, vcc
	v_cmp_le_i32_e32 vcc, v67, v185
	v_add_u32_e32 v67, 58, v187
	s_nop 0
	v_cndmask_b32_e32 v144, v206, v144, vcc
	v_cmp_le_i32_e32 vcc, v67, v185
	v_add_u32_e32 v67, 27, v187
	s_nop 0
	v_cndmask_b32_e32 v128, v206, v128, vcc
	v_cmp_le_i32_e32 vcc, v67, v185
	v_add_u32_e32 v67, 59, v187
	s_nop 0
	v_cndmask_b32_e32 v145, v206, v145, vcc
	v_cmp_le_i32_e32 vcc, v67, v185
	s_nop 1
	v_cndmask_b32_e32 v129, v206, v129, vcc
	s_branch .LBB0_797
.Lattn_rare_m0_a4:
	v_max_f32_e32 v82, v98, v98
	v_max_f32_e32 v98, 0, v82
	v_exp_f32_e64 v99, -v98
	v_add_f32_e32 v212, v212, v98
	v_xor_b32_e32 v82, 0x80000000, v212
	v_mov_b32_e32 v83, v82
	v_mov_b32_e32 v84, v82
	v_mov_b32_e32 v85, v82
	v_mov_b32_e32 v86, v82
	v_mov_b32_e32 v87, v82
	v_mov_b32_e32 v88, v82
	v_mov_b32_e32 v89, v82
	v_mov_b32_e32 v90, v82
	v_mov_b32_e32 v91, v82
	v_mov_b32_e32 v92, v82
	v_mov_b32_e32 v93, v82
	v_mov_b32_e32 v94, v82
	v_mov_b32_e32 v95, v82
	v_mov_b32_e32 v96, v82
	v_mov_b32_e32 v97, v82
	s_and_saveexec_b64 s[22:23], s[8:9]
	ds_write_b32 v1, v99
	s_or_b64 exec, exec, s[22:23]
	v_sub_f32_e32 v145, v145, v98
	v_sub_f32_e32 v144, v144, v98
	v_sub_f32_e32 v143, v143, v98
	v_sub_f32_e32 v142, v142, v98
	v_sub_f32_e32 v141, v141, v98
	v_sub_f32_e32 v140, v140, v98
	v_sub_f32_e32 v139, v139, v98
	v_sub_f32_e32 v138, v138, v98
	v_sub_f32_e32 v137, v137, v98
	v_sub_f32_e32 v136, v136, v98
	v_sub_f32_e32 v135, v135, v98
	v_sub_f32_e32 v134, v134, v98
	v_sub_f32_e32 v133, v133, v98
	v_sub_f32_e32 v132, v132, v98
	v_sub_f32_e32 v131, v131, v98
	v_sub_f32_e32 v130, v130, v98
	v_sub_f32_e32 v129, v129, v98
	v_sub_f32_e32 v128, v128, v98
	v_sub_f32_e32 v127, v127, v98
	v_sub_f32_e32 v126, v126, v98
	v_sub_f32_e32 v125, v125, v98
	v_sub_f32_e32 v124, v124, v98
	v_sub_f32_e32 v123, v123, v98
	v_sub_f32_e32 v122, v122, v98
	v_sub_f32_e32 v121, v121, v98
	v_sub_f32_e32 v120, v120, v98
	v_sub_f32_e32 v119, v119, v98
	v_sub_f32_e32 v118, v118, v98
	v_sub_f32_e32 v117, v117, v98
	v_sub_f32_e32 v116, v116, v98
	v_sub_f32_e32 v115, v115, v98
	v_sub_f32_e32 v114, v114, v98
	v_mul_f32_e32 v192, v192, v99
	s_branch .LBB0_806
.Lattn_rare_m0_b5:
	s_waitcnt lgkmcnt(0)
	ds_read_b128 v[124:127], v215 offset:96
	ds_read_b128 v[128:131], v215 offset:64
	ds_read_b128 v[132:135], v215
	ds_read_b128 v[136:139], v215 offset:32
	s_waitcnt lgkmcnt(0)
	s_waitcnt lgkmcnt(3)
	v_pk_mul_f32 v[32:33], v[32:33], v[126:127]
	v_pk_mul_f32 v[30:31], v[30:31], v[124:125]
	s_waitcnt lgkmcnt(2)
	v_pk_mul_f32 v[28:29], v[28:29], v[130:131]
	v_pk_mul_f32 v[26:27], v[26:27], v[128:129]
	s_waitcnt lgkmcnt(0)
	v_pk_mul_f32 v[24:25], v[24:25], v[138:139]
	v_pk_mul_f32 v[22:23], v[22:23], v[136:137]
	v_pk_mul_f32 v[20:21], v[20:21], v[134:135]
	v_pk_mul_f32 v[18:19], v[18:19], v[132:133]
	v_pk_mul_f32 v[64:65], v[64:65], v[126:127]
	v_pk_mul_f32 v[62:63], v[62:63], v[124:125]
	v_pk_mul_f32 v[60:61], v[60:61], v[130:131]
	v_pk_mul_f32 v[58:59], v[58:59], v[128:129]
	v_pk_mul_f32 v[56:57], v[56:57], v[138:139]
	v_pk_mul_f32 v[54:55], v[54:55], v[136:137]
	v_pk_mul_f32 v[52:53], v[52:53], v[134:135]
	v_pk_mul_f32 v[50:51], v[50:51], v[132:133]
	v_pk_mul_f32 v[48:49], v[48:49], v[126:127]
	v_pk_mul_f32 v[46:47], v[46:47], v[124:125]
	v_pk_mul_f32 v[44:45], v[44:45], v[130:131]
	v_pk_mul_f32 v[42:43], v[42:43], v[128:129]
	v_pk_mul_f32 v[40:41], v[40:41], v[138:139]
	v_pk_mul_f32 v[38:39], v[38:39], v[136:137]
	v_pk_mul_f32 v[36:37], v[36:37], v[134:135]
	v_pk_mul_f32 v[34:35], v[34:35], v[132:133]
	v_pk_mul_f32 v[16:17], v[16:17], v[126:127]
	v_pk_mul_f32 v[14:15], v[14:15], v[124:125]
	v_pk_mul_f32 v[12:13], v[12:13], v[130:131]
	v_pk_mul_f32 v[10:11], v[10:11], v[128:129]
	v_pk_mul_f32 v[8:9], v[8:9], v[138:139]
	v_pk_mul_f32 v[6:7], v[6:7], v[136:137]
	v_pk_mul_f32 v[4:5], v[4:5], v[134:135]
	v_pk_mul_f32 v[2:3], v[2:3], v[132:133]
	s_branch .LBB0_808
.Lattn_rare_m0_c6:
	v_add_u32_e32 v124, 0x60, v187
	v_add_u32_e32 v123, 64, v187
	v_cmp_le_i32_e32 vcc, v124, v185
	s_nop 1
	v_cndmask_b32_e32 v66, v206, v66, vcc
	v_cmp_lt_i32_e32 vcc, v123, v185
	s_nop 1
	v_cndmask_b32_e32 v99, v206, v99, vcc
	v_cmp_le_i32_e32 vcc, v123, v185
	v_add_u32_e32 v123, 0x61, v187
	s_nop 0
	v_cndmask_b32_e32 v98, v206, v98, vcc
	v_cmp_le_i32_e32 vcc, v123, v185
	v_add_u32_e32 v123, 0x42, v187
	s_nop 0
	v_cndmask_b32_e32 v67, v206, v67, vcc
	v_cmp_le_i32_e32 vcc, v123, v185
	v_add_u32_e32 v123, 0x62, v187
	s_nop 0
	v_cndmask_b32_e32 v100, v206, v100, vcc
	v_cmp_le_i32_e32 vcc, v123, v185
	v_add_u32_e32 v123, 0x43, v187
	s_nop 0
	v_cndmask_b32_e32 v68, v206, v68, vcc
	v_cmp_le_i32_e32 vcc, v123, v185
	v_add_u32_e32 v123, 0x63, v187
	s_nop 0
	v_cndmask_b32_e32 v101, v206, v101, vcc
	v_cmp_le_i32_e32 vcc, v123, v185
	v_add_u32_e32 v123, 0x48, v187
	s_nop 0
	v_cndmask_b32_e32 v69, v206, v69, vcc
	v_cmp_le_i32_e32 vcc, v123, v185
	v_add_u32_e32 v123, 0x68, v187
	s_nop 0
	v_cndmask_b32_e32 v102, v206, v102, vcc
	v_cmp_le_i32_e32 vcc, v123, v185
	v_add_u32_e32 v123, 0x49, v187
	s_nop 0
	v_cndmask_b32_e32 v70, v206, v70, vcc
	v_cmp_le_i32_e32 vcc, v123, v185
	v_add_u32_e32 v123, 0x69, v187
	s_nop 0
	v_cndmask_b32_e32 v103, v206, v103, vcc
	v_cmp_le_i32_e32 vcc, v123, v185
	v_add_u32_e32 v123, 0x4a, v187
	s_nop 0
	v_cndmask_b32_e32 v71, v206, v71, vcc
	v_cmp_le_i32_e32 vcc, v123, v185
	v_add_u32_e32 v123, 0x6a, v187
	s_nop 0
	v_cndmask_b32_e32 v104, v206, v104, vcc
	v_cmp_le_i32_e32 vcc, v123, v185
	v_add_u32_e32 v123, 0x4b, v187
	s_nop 0
	v_cndmask_b32_e32 v72, v206, v72, vcc
	v_cmp_le_i32_e32 vcc, v123, v185
	v_add_u32_e32 v123, 0x6b, v187
	s_nop 0
	v_cndmask_b32_e32 v105, v206, v105, vcc
	v_cmp_le_i32_e32 vcc, v123, v185
	v_add_u32_e32 v123, 0x50, v187
	s_nop 0
	v_cndmask_b32_e32 v73, v206, v73, vcc
	v_cmp_le_i32_e32 vcc, v123, v185
	v_add_u32_e32 v123, 0x70, v187
	s_nop 0
	v_cndmask_b32_e32 v106, v206, v106, vcc
	v_cmp_le_i32_e32 vcc, v123, v185
	v_add_u32_e32 v123, 0x51, v187
	s_nop 0
	v_cndmask_b32_e32 v74, v206, v74, vcc
	v_cmp_le_i32_e32 vcc, v123, v185
	v_add_u32_e32 v123, 0x71, v187
	s_nop 0
	v_cndmask_b32_e32 v107, v206, v107, vcc
	v_cmp_le_i32_e32 vcc, v123, v185
	v_add_u32_e32 v123, 0x52, v187
	s_nop 0
	v_cndmask_b32_e32 v75, v206, v75, vcc
	v_cmp_le_i32_e32 vcc, v123, v185
	v_add_u32_e32 v123, 0x72, v187
	s_nop 0
	v_cndmask_b32_e32 v108, v206, v108, vcc
	v_cmp_le_i32_e32 vcc, v123, v185
	v_add_u32_e32 v123, 0x53, v187
	s_nop 0
	v_cndmask_b32_e32 v76, v206, v76, vcc
	v_cmp_le_i32_e32 vcc, v123, v185
	v_add_u32_e32 v123, 0x73, v187
	s_nop 0
	v_cndmask_b32_e32 v109, v206, v109, vcc
	v_cmp_le_i32_e32 vcc, v123, v185
	v_add_u32_e32 v123, 0x58, v187
	s_nop 0
	v_cndmask_b32_e32 v77, v206, v77, vcc
	v_cmp_le_i32_e32 vcc, v123, v185
	v_add_u32_e32 v123, 0x78, v187
	s_nop 0
	v_cndmask_b32_e32 v110, v206, v110, vcc
	v_cmp_le_i32_e32 vcc, v123, v185
	v_add_u32_e32 v123, 0x59, v187
	s_nop 0
	v_cndmask_b32_e32 v78, v206, v78, vcc
	v_cmp_le_i32_e32 vcc, v123, v185
	v_add_u32_e32 v123, 0x79, v187
	s_nop 0
	v_cndmask_b32_e32 v111, v206, v111, vcc
	v_cmp_le_i32_e32 vcc, v123, v185
	v_add_u32_e32 v123, 0x5a, v187
	s_nop 0
	v_cndmask_b32_e32 v79, v206, v79, vcc
	v_cmp_le_i32_e32 vcc, v123, v185
	v_add_u32_e32 v123, 0x7a, v187
	s_nop 0
	v_cndmask_b32_e32 v112, v206, v112, vcc
	v_cmp_le_i32_e32 vcc, v123, v185
	v_add_u32_e32 v123, 0x5b, v187
	s_nop 0
	v_cndmask_b32_e32 v80, v206, v80, vcc
	v_cmp_le_i32_e32 vcc, v123, v185
	v_add_u32_e32 v123, 0x7b, v187
	s_nop 0
	v_cndmask_b32_e32 v113, v206, v113, vcc
	v_cmp_le_i32_e32 vcc, v123, v185
	s_nop 1
	v_cndmask_b32_e32 v81, v206, v81, vcc
	s_branch .LBB0_810

.LBB0_818:
	s_mulk_i32 s50, 0x6000
	s_sub_i32 s4, s56, s50
	s_add_i32 s4, s14, s4
	s_addk_i32 s4, 0xc000
	v_lshl_add_u64 v[68:69], v[192:193], 0, s[44:45]
	s_mov_b32 m0, s4
	s_nop 0
	global_load_lds_dwordx4 v[68:69], off
	s_andn2_b64 vcc, exec, s[94:95]
	s_cbranch_vccz .LBB0_801
	s_branch .LBB0_802

.LBB0_823:
	s_mov_b64 s[6:7], 0x60000
	v_lshl_add_u64 v[44:45], v[188:189], 0, s[6:7]
	s_mov_b32 m0, s56
	s_nop 0
	global_load_lds_dwordx4 v[44:45], off
	v_cndmask_b32_e64 v43, 0, 1, s[4:5]
	v_cmp_ne_u32_e64 s[6:7], 1, v43
	s_andn2_b64 vcc, exec, s[4:5]
	s_cbranch_vccz .LBB0_776
	s_branch .LBB0_777

.LBB0_826:
	s_mov_b64 s[22:23], s[0:1]
	s_waitcnt vmcnt(0) lgkmcnt(0)
	s_barrier
	s_load_dwordx2 s[22:23], s[22:23], 0xa0
	s_lshl_b64 s[4:5], s[62:63], 23
	s_lshl_b64 s[92:93], s[4:5], 1
	v_lshlrev_b32_e32 v83, 10, v207
	v_lshlrev_b32_e32 v82, 10, v211
	s_waitcnt lgkmcnt(0)
	s_add_u32 s4, s22, s92
	s_addc_u32 s5, s23, s93
	s_add_u32 s4, s4, s64
	v_lshlrev_b32_e32 v84, 1, v83
	v_mov_b32_e32 v85, v146
	s_addc_u32 s5, s5, s65
	v_lshlrev_b32_e32 v82, 1, v82
	v_mov_b32_e32 v83, v146
	s_ashr_i32 s61, s60, 31
	v_lshl_add_u64 v[84:85], s[4:5], 0, v[84:85]
	v_lshl_add_u64 v[82:83], s[4:5], 0, v[82:83]
	s_lshl_b64 s[4:5], s[60:61], 8
	s_add_u32 s61, s4, s86
	s_addc_u32 s63, s5, s87
	s_add_u32 s4, s61, s13
	s_addc_u32 s5, s63, s24
	s_lshl_b64 s[4:5], s[4:5], 11
	s_add_u32 s4, s22, s4
	v_lshl_add_u64 v[84:85], s[88:89], 1, v[84:85]
	s_mov_b64 s[28:29], 0x8800080
	v_lshl_add_u64 v[82:83], s[90:91], 1, v[82:83]
	v_mov_b32_e32 v187, v146
	s_addc_u32 s5, s23, s5
	v_lshl_add_u64 v[86:87], v[84:85], 0, s[28:29]
	v_lshl_add_u64 v[82:83], v[82:83], 0, v[186:187]
	s_add_u32 s4, s4, s64
	s_mov_b32 m0, s56
	s_nop 0
	global_load_lds_dwordx4 v[86:87], off
	v_lshl_add_u64 v[88:89], v[82:83], 0, s[58:59]
	s_addc_u32 s5, s5, s65
	s_mov_b32 m0, s55
	s_nop 0
	global_load_lds_dwordx4 v[88:89], off
	s_mov_b64 s[22:23], 0xc800080
	v_lshl_add_u64 v[86:87], v[82:83], 0, s[22:23]
	s_mov_b32 m0, s54
	s_nop 0
	global_load_lds_dwordx4 v[86:87], off
	s_cmp_lg_u32 0, -1
	s_mov_b64 s[22:23], 0x8820080
	s_cselect_b32 s9, 0, 0
	v_lshl_add_u64 v[86:87], v[84:85], 0, s[22:23]
	s_add_i32 s9, s9, s25
	s_mov_b64 s[22:23], 0xc820000
	s_add_i32 s13, s9, 0x2000
	s_mov_b32 m0, s13
	s_nop 0
	global_load_lds_dwordx4 v[86:87], off
	v_lshl_add_u64 v[86:87], v[82:83], 0, s[22:23]
	s_mov_b64 s[22:23], 0xc820080
	s_add_i32 s13, s9, 0x8000
	s_mov_b32 m0, s13
	s_nop 0
	global_load_lds_dwordx4 v[86:87], off
	v_lshl_add_u64 v[82:83], v[82:83], 0, s[22:23]
	s_mov_b64 s[22:23], 0x8840080
	s_add_i32 s13, s9, 0x10000
	s_mov_b32 m0, s13
	s_nop 0
	global_load_lds_dwordx4 v[82:83], off
	v_lshl_add_u64 v[82:83], v[84:85], 0, s[22:23]
	v_mov_b32_e32 v185, v146
	s_addk_i32 s9, 0x4000
	s_mov_b32 m0, s9
	s_nop 0
	global_load_lds_dwordx4 v[82:83], off
	v_lshl_add_u64 v[82:83], s[4:5], 0, v[184:185]
	v_lshl_add_u64 v[82:83], v[82:83], 0, s[30:31]
	global_load_dwordx4 v[148:151], v[82:83], off offset:128
	global_load_dwordx4 v[152:155], v[82:83], off offset:160
	global_load_dwordx4 v[156:159], v[82:83], off offset:192
	global_load_dwordx4 v[160:163], v[82:83], off offset:224
	v_add_u32_e32 v122, s8, v147
	ds_read_b64_tr_b16 v[82:83], v122 offset:24576
	ds_read_b64_tr_b16 v[84:85], v122 offset:25088
	ds_read_b64_tr_b16 v[86:87], v122 offset:28672
	ds_read_b64_tr_b16 v[88:89], v122 offset:29184
	s_waitcnt lgkmcnt(2)
	v_mfma_f32_32x32x16_bf16 v[18:33], v[164:167], v[82:85], v[18:33]
	ds_read_b64_tr_b16 v[90:91], v122 offset:57344
	ds_read_b64_tr_b16 v[92:93], v122 offset:57856
	s_waitcnt lgkmcnt(2)
	v_mfma_f32_32x32x16_bf16 v[50:65], v[164:167], v[86:89], v[50:65]
	ds_read_b64_tr_b16 v[82:83], v122 offset:61440
	ds_read_b64_tr_b16 v[84:85], v122 offset:61952
	s_waitcnt lgkmcnt(2)
	v_mfma_f32_32x32x16_bf16 v[34:49], v[164:167], v[90:93], v[34:49]
	ds_read_b64_tr_b16 v[118:119], v122 offset:25600
	ds_read_b64_tr_b16 v[120:121], v122 offset:26112
	s_waitcnt lgkmcnt(2)
	v_mfma_f32_32x32x16_bf16 v[2:17], v[164:167], v[82:85], v[2:17]
	ds_read_b64_tr_b16 v[114:115], v122 offset:29696
	ds_read_b64_tr_b16 v[116:117], v122 offset:30208
	v_max_f32_e32 v82, v98, v99
	v_max3_f32 v83, v100, v101, v67
	v_max3_f32 v82, v82, v66, v68
	v_max3_f32 v82, v82, v69, v102
	v_max3_f32 v83, v83, v104, v105
	v_max3_f32 v82, v82, v103, v70
	v_max3_f32 v83, v83, v72, v73
	v_max3_f32 v82, v82, v71, v106
	v_max3_f32 v83, v83, v108, v109
	v_max3_f32 v82, v82, v107, v74
	v_max3_f32 v83, v83, v76, v77
	v_max3_f32 v82, v82, v75, v110
	v_max3_f32 v83, v83, v112, v113
	v_max3_f32 v82, v82, v111, v78
	v_max3_f32 v83, v83, v80, v81
	v_max3_f32 v82, v82, v79, v83
	v_mov_b32_e32 v83, v82
	s_nop 1
	v_permlane32_swap_b32_e32 v82, v83
	v_max_f32_e32 v82, v82, v83
	v_cmp_lt_f32_e32 vcc, s15, v82
	s_cmp_lg_u64 vcc, 0
	s_cselect_b64 s[8:9], -1, 0
	s_cbranch_vccz .LBB0_830
	v_max_f32_e32 v82, v82, v82
	v_max_f32_e32 v123, 0, v82
	v_add_f32_e32 v82, v212, v123
	v_xor_b32_e32 v82, 0x80000000, v82
	v_mov_b32_e32 v83, v82
	v_mov_b32_e32 v84, v82
	v_mov_b32_e32 v85, v82
	v_mov_b32_e32 v86, v82
	v_mov_b32_e32 v87, v82
	v_mov_b32_e32 v88, v82
	v_mov_b32_e32 v89, v82
	v_mov_b32_e32 v90, v82
	v_mov_b32_e32 v91, v82
	v_mov_b32_e32 v92, v82
	v_mov_b32_e32 v93, v82
	v_mov_b32_e32 v94, v82
	v_mov_b32_e32 v95, v82
	v_mov_b32_e32 v96, v82
	v_mov_b32_e32 v97, v82
	v_cmp_gt_u32_e32 vcc, 32, v207
	v_exp_f32_e64 v82, -v123
	s_and_saveexec_b64 s[4:5], vcc
	s_mov_b64 s[86:87], 0x14800000
	ds_write_b32 v1, v82
	s_or_b64 exec, exec, s[4:5]
	v_sub_f32_e32 v113, v113, v123
	v_sub_f32_e32 v112, v112, v123
	v_sub_f32_e32 v111, v111, v123
	v_sub_f32_e32 v110, v110, v123
	v_sub_f32_e32 v109, v109, v123
	v_sub_f32_e32 v108, v108, v123
	v_sub_f32_e32 v107, v107, v123
	v_sub_f32_e32 v106, v106, v123
	v_sub_f32_e32 v105, v105, v123
	v_sub_f32_e32 v104, v104, v123
	v_sub_f32_e32 v103, v103, v123
	v_sub_f32_e32 v102, v102, v123
	v_sub_f32_e32 v101, v101, v123
	v_sub_f32_e32 v100, v100, v123
	v_sub_f32_e32 v99, v99, v123
	v_sub_f32_e32 v98, v98, v123
	v_sub_f32_e32 v81, v81, v123
	v_sub_f32_e32 v80, v80, v123
	v_sub_f32_e32 v79, v79, v123
	v_sub_f32_e32 v78, v78, v123
	v_sub_f32_e32 v77, v77, v123
	v_sub_f32_e32 v76, v76, v123
	v_sub_f32_e32 v75, v75, v123
	v_sub_f32_e32 v74, v74, v123
	v_sub_f32_e32 v73, v73, v123
	v_sub_f32_e32 v72, v72, v123
	v_sub_f32_e32 v71, v71, v123
	v_sub_f32_e32 v70, v70, v123
	v_sub_f32_e32 v69, v69, v123
	v_sub_f32_e32 v68, v68, v123
	v_sub_f32_e32 v67, v67, v123
	v_sub_f32_e32 v66, v66, v123
	v_mul_f32_e32 v213, v213, v82
	s_branch .LBB0_831

.LBB0_841:
	s_add_u32 s4, s22, s92
	s_addc_u32 s5, s23, s93
	s_add_u32 s4, s4, s64
	v_and_b32_e32 v1, 63, v34
	s_addc_u32 s5, s5, s65
	s_lshl_b32 s8, s12, 3
	v_lshlrev_b32_e32 v42, 11, v1
	v_mov_b32_e32 v43, v146
	s_ashr_i32 s9, s8, 31
	s_lshl_b32 s24, s12, 10
	v_lshl_add_u64 v[42:43], s[4:5], 0, v[42:43]
	s_cmp_lg_u32 0, -1
	v_lshl_add_u64 v[42:43], s[8:9], 1, v[42:43]
	s_cselect_b32 s4, 0, 0
	v_lshl_add_u64 v[188:189], v[42:43], 0, s[28:29]
	s_andn2_b64 vcc, exec, s[78:79]
	s_add_i32 s25, s24, s4
	s_cbranch_vccnz .LBB0_843
	s_mov_b64 s[4:5], 0x60000
	v_lshl_add_u64 v[42:43], v[188:189], 0, s[4:5]
	s_mov_b32 m0, s25
	s_nop 0
	global_load_lds_dwordx4 v[42:43], off
.LBB0_843:
	s_lshl_b32 s4, s12, 4
	v_lshrrev_b32_e32 v39, 2, v1
	v_and_or_b32 v41, s4, 48, v39
	s_ashr_i32 s4, s14, 3
	v_lshlrev_b32_e32 v211, 3, v34
	v_lshlrev_b32_e32 v42, 10, v41
	s_and_b32 s78, s4, 0xffffffe0
	v_and_b32_e32 v41, 24, v211
	s_ashr_i32 s79, s78, 31
	s_and_b64 vcc, exec, s[6:7]
	v_lshlrev_b32_e32 v186, 1, v42
	v_lshlrev_b32_e32 v184, 1, v41
	s_cbranch_vccnz .LBB0_845
	s_add_u32 s4, s22, s92
	s_addc_u32 s5, s23, s93
	s_add_u32 s4, s4, s64
	s_addc_u32 s5, s5, s65
	v_mov_b32_e32 v187, v146
	v_lshl_add_u64 v[42:43], s[4:5], 0, v[186:187]
	v_lshl_add_u64 v[42:43], s[78:79], 1, v[42:43]
	v_mov_b32_e32 v185, v146
	v_lshl_add_u64 v[42:43], v[42:43], 0, v[184:185]
	s_mov_b64 s[4:5], 0xc840000
	s_cmp_lg_u32 0, -1
	v_lshl_add_u64 v[44:45], v[42:43], 0, s[4:5]
	s_cselect_b32 s4, 0, 0
	s_add_i32 s20, s4, s24
	s_add_i32 s4, s20, 0xa000
	s_mov_b32 m0, s4
	s_nop 0
	global_load_lds_dwordx4 v[44:45], off
	s_mov_b64 s[4:5], 0xc840080
	v_lshl_add_u64 v[42:43], v[42:43], 0, s[4:5]
	s_add_i32 s20, s20, 0x12000
	s_mov_b32 m0, s20
	s_nop 0
	global_load_lds_dwordx4 v[42:43], off

.LBB0_849:
	s_cmp_lt_i32 s30, s71
	s_cselect_b64 s[4:5], -1, 0
	s_cselect_b64 s[80:81], 0, -1
	s_cbranch_scc0 .Lattn_head_rare_m1
	s_waitcnt vmcnt(3) lgkmcnt(0)
	s_barrier
.LBB0_853:
	s_add_i32 s22, s30, 1
	s_cmp_lt_i32 s22, s71
	s_cselect_b64 s[76:77], -1, 0
	s_cselect_b64 s[22:23], 0, -1
	v_lshl_add_u64 v[192:193], v[188:189], 0, s[74:75]
	s_cbranch_scc0 .LBB0_855
	s_mul_hi_u32 s28, s31, 0xaaaaaaab
	s_lshr_b32 s28, s28, 1
	s_mulk_i32 s28, 0x6000
	s_sub_i32 s28, s25, s28
	s_add_i32 s28, s14, s28
	v_lshl_add_u64 v[114:115], v[192:193], 0, s[38:39]
	s_addk_i32 s28, 0xa000
	s_mov_b32 m0, s28
	s_nop 0
	global_load_lds_dwordx4 v[114:115], off
.LBB0_855:
	s_andn2_b64 vcc, exec, s[4:5]
	v_lshl_add_u64 v[194:195], v[190:191], 0, s[74:75]
	s_cbranch_vccnz .LBB0_857
	s_add_i32 s4, s14, 0xffffe000
	s_and_b32 s4, s4, 0x6000
	s_add_i32 s5, s4, s54
	v_lshl_add_u64 v[114:115], v[194:195], 0, s[40:41]
	s_add_i32 s4, s4, s55
	s_mov_b32 m0, s4
	s_nop 0
	global_load_lds_dwordx4 v[114:115], off
	v_lshl_add_u64 v[116:117], v[194:195], 0, s[42:43]
	s_mov_b32 m0, s5
	s_nop 0
	global_load_lds_dwordx4 v[116:117], off
.LBB0_857:
	s_mul_hi_u32 s4, s56, 0xaaaaaaab
	s_lshr_b32 s50, s4, 1
	s_mul_i32 s4, s50, 0xffffa000
	s_add_i32 s4, s14, s4
	s_and_b32 s51, s14, 0x6000
	v_add_u32_e32 v216, s4, v187
	v_add_u32_e32 v215, s51, v209
	v_add_u32_e32 v216, 0xffffc000, v216
	ds_read_b64_tr_b16 v[118:119], v215 offset:24576
	ds_read_b64_tr_b16 v[120:121], v215 offset:25088
	ds_read_b64_tr_b16 v[122:123], v215 offset:28672
	ds_read_b64_tr_b16 v[124:125], v215 offset:29184
	ds_read_b128 v[114:117], v216
	s_waitcnt lgkmcnt(3)
	v_mfma_f32_32x32x16_bf16 v[18:33], v[164:167], v[118:121], v[18:33]
	ds_read_b64_tr_b16 v[126:127], v215 offset:57344
	ds_read_b64_tr_b16 v[128:129], v215 offset:57856
	s_waitcnt lgkmcnt(3)
	v_mfma_f32_32x32x16_bf16 v[50:65], v[164:167], v[122:125], v[50:65]
	ds_read_b64_tr_b16 v[130:131], v215 offset:61440
	ds_read_b64_tr_b16 v[132:133], v215 offset:61952
	s_waitcnt lgkmcnt(2)
	v_mfma_f32_32x32x16_bf16 v[34:49], v[164:167], v[126:129], v[34:49]
	ds_read_b64_tr_b16 v[118:119], v215 offset:25600
	ds_read_b64_tr_b16 v[120:121], v215 offset:26112
	s_waitcnt lgkmcnt(2)
	v_mfma_f32_32x32x16_bf16 v[2:17], v[164:167], v[130:133], v[2:17]
	ds_read_b64_tr_b16 v[180:181], v215 offset:29696
	ds_read_b64_tr_b16 v[182:183], v215 offset:30208
	v_max_f32_e32 v122, v98, v99
	v_max3_f32 v123, v100, v101, v67
	v_max3_f32 v122, v122, v66, v68
	v_max3_f32 v122, v122, v69, v102
	v_max3_f32 v123, v123, v104, v105
	v_max3_f32 v122, v122, v103, v70
	v_max3_f32 v123, v123, v72, v73
	v_max3_f32 v122, v122, v71, v106
	v_max3_f32 v123, v123, v108, v109
	v_max3_f32 v122, v122, v107, v74
	v_max3_f32 v123, v123, v76, v77
	v_max3_f32 v122, v122, v75, v110
	v_max3_f32 v123, v123, v112, v113
	v_max3_f32 v122, v122, v111, v78
	v_max3_f32 v123, v123, v80, v81
	v_max3_f32 v122, v122, v79, v123
	v_mov_b32_e32 v123, v122
	s_nop 1
	v_permlane32_swap_b32_e32 v122, v123
	v_max_f32_e32 v122, v122, v123
	v_cmp_lt_f32_e32 vcc, s15, v122
	s_cmp_lg_u64 vcc, 0
	s_cselect_b64 s[4:5], -1, 0
	s_cbranch_vccnz .Lattn_rare_m1_a1
.LBB0_861:
	v_exp_f32_e32 v164, v98
	v_mfma_f32_32x32x16_bf16 v[130:145], v[114:117], v[148:151], v[82:97]
	v_exp_f32_e32 v165, v99
	v_exp_f32_e32 v217, v100
	ds_read_b64_tr_b16 v[218:219], v215 offset:58368
	ds_read_b64_tr_b16 v[220:221], v215 offset:58880
	v_exp_f32_e32 v230, v101
	ds_read_b128 v[222:225], v216 offset:512
	s_waitcnt lgkmcnt(5)
	v_mfma_f32_32x32x16_bf16 v[18:33], v[168:171], v[118:121], v[18:33]
	v_add_f32_e32 v98, v165, v164
	v_add_f32_e32 v98, v217, v98
	v_add_f32_e32 v231, v230, v98
	ds_read_b64_tr_b16 v[98:99], v215 offset:62464
	ds_read_b64_tr_b16 v[100:101], v215 offset:62976
	ds_read_b128 v[226:229], v216 offset:2048
	v_exp_f32_e32 v232, v102
	s_waitcnt lgkmcnt(3)
	v_mfma_f32_32x32x16_bf16 v[114:129], v[222:225], v[148:151], v[82:97]
	v_exp_f32_e32 v222, v103
	v_exp_f32_e32 v223, v104
	v_exp_f32_e32 v224, v105
	v_add_f32_e32 v102, v232, v231
	v_add_f32_e32 v102, v222, v102
	v_add_f32_e32 v102, v223, v102
	v_add_f32_e32 v225, v224, v102
	v_mfma_f32_32x32x16_bf16 v[50:65], v[168:171], v[180:183], v[50:65]
	v_exp_f32_e32 v231, v106
	s_waitcnt lgkmcnt(0)
	v_mfma_f32_32x32x16_bf16 v[130:145], v[226:229], v[152:155], v[130:145]
	v_exp_f32_e32 v233, v107
	v_exp_f32_e32 v226, v108
	ds_read_b64_tr_b16 v[102:103], v215 offset:26624
	ds_read_b64_tr_b16 v[104:105], v215 offset:27136
	v_exp_f32_e32 v227, v109
	ds_read_b128 v[180:183], v216 offset:2560
	v_add_f32_e32 v106, v231, v225
	v_mfma_f32_32x32x16_bf16 v[34:49], v[168:171], v[218:221], v[34:49]
	v_add_f32_e32 v106, v233, v106
	v_add_f32_e32 v106, v226, v106
	v_add_f32_e32 v225, v227, v106
	v_cvt_pk_bf16_f32 v164, v164, v165
	v_cvt_pk_bf16_f32 v165, v217, v230
	v_exp_f32_e32 v217, v110
	s_waitcnt lgkmcnt(0)
	v_mfma_f32_32x32x16_bf16 v[114:129], v[180:183], v[152:155], v[114:129]
	v_exp_f32_e32 v228, v111
	v_exp_f32_e32 v180, v112
	ds_read_b64_tr_b16 v[106:107], v215 offset:30720
	ds_read_b64_tr_b16 v[108:109], v215 offset:31232
	v_exp_f32_e32 v181, v113
	ds_read_b128 v[218:221], v216 offset:4096
	v_add_f32_e32 v110, v217, v225
	v_mfma_f32_32x32x16_bf16 v[2:17], v[168:171], v[98:101], v[2:17]
	v_add_f32_e32 v110, v228, v110
	v_add_f32_e32 v110, v180, v110
	v_add_f32_e32 v182, v181, v110
	v_cvt_pk_bf16_f32 v166, v232, v222
	v_cvt_pk_bf16_f32 v167, v223, v224
	s_waitcnt lgkmcnt(0)
	v_mfma_f32_32x32x16_bf16 v[130:145], v[218:221], v[156:159], v[130:145]
	v_exp_f32_e32 v183, v66
	ds_read_b64_tr_b16 v[98:99], v215 offset:59392
	ds_read_b64_tr_b16 v[100:101], v215 offset:59904
	v_exp_f32_e32 v222, v67
	ds_read_b128 v[110:113], v216 offset:4608
	v_add_f32_e32 v66, v183, v182
	v_cvt_pk_bf16_f32 v168, v231, v233
	v_mfma_f32_32x32x16_bf16 v[18:33], v[172:175], v[102:105], v[18:33]
	v_add_f32_e32 v66, v222, v66
	v_cvt_pk_bf16_f32 v169, v226, v227
	v_mfma_f32_32x32x16_bf16 v[50:65], v[172:175], v[106:109], v[50:65]
	v_exp_f32_e32 v182, v68
	ds_read_b64_tr_b16 v[102:103], v215 offset:63488
	ds_read_b64_tr_b16 v[104:105], v215 offset:64000
	v_exp_f32_e32 v218, v69
	v_cvt_pk_bf16_f32 v170, v217, v228
	v_add_f32_e32 v66, v182, v66
	v_cvt_pk_bf16_f32 v171, v180, v181
	v_add_f32_e32 v219, v218, v66
	s_waitcnt lgkmcnt(2)
	v_mfma_f32_32x32x16_bf16 v[114:129], v[110:113], v[156:159], v[114:129]
	v_exp_f32_e32 v110, v70
	ds_read_b64_tr_b16 v[66:67], v215 offset:27648
	ds_read_b64_tr_b16 v[68:69], v215 offset:28160
	v_exp_f32_e32 v111, v71
	ds_read_b128 v[106:109], v216 offset:6144
	v_add_f32_e32 v70, v110, v219
	v_add_f32_e32 v70, v111, v70
	v_mfma_f32_32x32x16_bf16 v[34:49], v[172:175], v[98:101], v[34:49]
	s_waitcnt lgkmcnt(3)
	v_mfma_f32_32x32x16_bf16 v[2:17], v[172:175], v[102:105], v[2:17]
	v_exp_f32_e32 v112, v72
	ds_read_b64_tr_b16 v[98:99], v215 offset:31744
	ds_read_b64_tr_b16 v[100:101], v215 offset:32256
	v_exp_f32_e32 v113, v73
	v_add_f32_e32 v70, v112, v70
	v_add_f32_e32 v172, v113, v70
	s_waitcnt lgkmcnt(2)
	v_mfma_f32_32x32x16_bf16 v[130:145], v[106:109], v[160:163], v[130:145]
	v_exp_f32_e32 v74, v74
	ds_read_b64_tr_b16 v[70:71], v215 offset:60416
	ds_read_b64_tr_b16 v[72:73], v215 offset:60928
	v_exp_f32_e32 v75, v75
	ds_read_b128 v[102:105], v216 offset:6656
	v_add_f32_e32 v106, v74, v172
	v_cvt_pk_bf16_f32 v172, v183, v222
	v_mfma_f32_32x32x16_bf16 v[18:33], v[176:179], v[66:69], v[18:33]
	v_add_f32_e32 v106, v75, v106
	v_cvt_pk_bf16_f32 v173, v182, v218
	s_waitcnt lgkmcnt(3)
	v_mfma_f32_32x32x16_bf16 v[50:65], v[176:179], v[98:101], v[50:65]
	v_exp_f32_e32 v76, v76
	v_exp_f32_e32 v77, v77
	ds_read_b64_tr_b16 v[66:67], v215 offset:64512
	ds_read_b64_tr_b16 v[68:69], v215 offset:65024
	v_cvt_pk_bf16_f32 v174, v110, v111
	v_add_f32_e32 v106, v76, v106
	v_add_f32_e32 v106, v77, v106
	v_cvt_pk_bf16_f32 v175, v112, v113
	s_waitcnt lgkmcnt(2)
	v_mfma_f32_32x32x16_bf16 v[114:129], v[102:105], v[160:163], v[114:129]
	v_exp_f32_e32 v78, v78
	v_exp_f32_e32 v79, v79
	v_add_f32_e32 v98, v78, v106
	v_add_f32_e32 v98, v79, v98
	v_mfma_f32_32x32x16_bf16 v[34:49], v[176:179], v[70:73], v[34:49]
	s_waitcnt lgkmcnt(0)
	v_mfma_f32_32x32x16_bf16 v[2:17], v[176:179], v[66:69], v[2:17]
	v_exp_f32_e32 v80, v80
	v_exp_f32_e32 v81, v81
	v_add_f32_e32 v66, v80, v98
	v_add_f32_e32 v66, v81, v66
	s_andn2_b64 vcc, exec, s[4:5]
	s_cbranch_vccz .Lattn_rare_m1_b2

.LBB0_870:
	s_mul_hi_u32 s4, s30, 0xaaaaaaab
	s_lshr_b32 s4, s4, 1
	s_mulk_i32 s4, 0xa000
	s_add_i32 s5, s14, 0xffffa000
	s_add_i32 s4, s14, s4
	s_and_b32 s5, s5, 0x6000
	v_add_u32_e32 v194, s4, v187
	v_add_f32_e32 v192, v213, v66
	v_add_u32_e32 v193, s5, v209
	v_add_u32_e32 v194, 0xffffe000, v194
	ds_read_b64_tr_b16 v[70:71], v193 offset:24576
	ds_read_b64_tr_b16 v[72:73], v193 offset:25088
	ds_read_b64_tr_b16 v[98:99], v193 offset:28672
	ds_read_b64_tr_b16 v[100:101], v193 offset:29184
	ds_read_b128 v[66:69], v194
	s_waitcnt lgkmcnt(3)
	v_mfma_f32_32x32x16_bf16 v[18:33], v[164:167], v[70:73], v[18:33]
	ds_read_b64_tr_b16 v[102:103], v193 offset:57344
	ds_read_b64_tr_b16 v[104:105], v193 offset:57856
	s_waitcnt lgkmcnt(3)
	v_mfma_f32_32x32x16_bf16 v[50:65], v[164:167], v[98:101], v[50:65]
	ds_read_b64_tr_b16 v[106:107], v193 offset:61440
	ds_read_b64_tr_b16 v[108:109], v193 offset:61952
	s_waitcnt lgkmcnt(2)
	v_mfma_f32_32x32x16_bf16 v[34:49], v[164:167], v[102:105], v[34:49]
	ds_read_b64_tr_b16 v[70:71], v193 offset:25600
	ds_read_b64_tr_b16 v[72:73], v193 offset:26112
	s_waitcnt lgkmcnt(2)
	v_mfma_f32_32x32x16_bf16 v[2:17], v[164:167], v[106:109], v[2:17]
	ds_read_b64_tr_b16 v[180:181], v193 offset:29696
	ds_read_b64_tr_b16 v[182:183], v193 offset:30208
	v_max_f32_e32 v98, v130, v131
	v_max3_f32 v99, v132, v133, v115
	v_max3_f32 v98, v98, v114, v116
	v_max3_f32 v98, v98, v117, v134
	v_max3_f32 v99, v99, v136, v137
	v_max3_f32 v98, v98, v135, v118
	v_max3_f32 v99, v99, v120, v121
	v_max3_f32 v98, v98, v119, v138
	v_max3_f32 v99, v99, v140, v141
	v_max3_f32 v98, v98, v139, v122
	v_max3_f32 v99, v99, v124, v125
	v_max3_f32 v98, v98, v123, v142
	v_max3_f32 v99, v99, v144, v145
	v_max3_f32 v98, v98, v143, v126
	v_max3_f32 v99, v99, v128, v129
	v_max3_f32 v98, v98, v127, v99
	v_mov_b32_e32 v99, v98
	s_nop 1
	v_permlane32_swap_b32_e32 v98, v99
	v_max_f32_e32 v98, v98, v99
	v_cmp_lt_f32_e32 vcc, s15, v98
	s_cmp_lg_u64 vcc, 0
	s_cselect_b64 s[4:5], -1, 0
	s_cbranch_vccnz .Lattn_rare_m1_a4
.LBB0_874:
	v_cvt_pk_bf16_f32 v176, v74, v75
	v_cvt_pk_bf16_f32 v177, v76, v77
	v_cvt_pk_bf16_f32 v178, v78, v79
	v_cvt_pk_bf16_f32 v179, v80, v81
	v_exp_f32_e32 v164, v130
	v_mfma_f32_32x32x16_bf16 v[98:113], v[66:69], v[148:151], v[82:97]
	v_exp_f32_e32 v165, v131
	v_exp_f32_e32 v195, v132
	ds_read_b64_tr_b16 v[216:217], v193 offset:58368
	ds_read_b64_tr_b16 v[218:219], v193 offset:58880
	v_exp_f32_e32 v213, v133
	ds_read_b128 v[220:223], v194 offset:512
	s_waitcnt lgkmcnt(5)
	v_mfma_f32_32x32x16_bf16 v[18:33], v[168:171], v[70:73], v[18:33]
	v_add_f32_e32 v66, v165, v164
	v_add_f32_e32 v66, v195, v66
	v_add_f32_e32 v215, v213, v66
	ds_read_b64_tr_b16 v[130:131], v193 offset:62464
	ds_read_b64_tr_b16 v[132:133], v193 offset:62976
	ds_read_b128 v[224:227], v194 offset:2048
	v_exp_f32_e32 v228, v134
	s_waitcnt lgkmcnt(3)
	v_mfma_f32_32x32x16_bf16 v[66:81], v[220:223], v[148:151], v[82:97]
	v_exp_f32_e32 v220, v135
	v_exp_f32_e32 v221, v136
	v_exp_f32_e32 v222, v137
	v_add_f32_e32 v134, v228, v215
	v_add_f32_e32 v134, v220, v134
	v_add_f32_e32 v134, v221, v134
	v_add_f32_e32 v215, v222, v134
	v_mfma_f32_32x32x16_bf16 v[50:65], v[168:171], v[180:183], v[50:65]
	v_exp_f32_e32 v223, v138
	s_waitcnt lgkmcnt(0)
	v_mfma_f32_32x32x16_bf16 v[98:113], v[224:227], v[152:155], v[98:113]
	v_exp_f32_e32 v229, v139
	v_exp_f32_e32 v224, v140
	ds_read_b64_tr_b16 v[134:135], v193 offset:26624
	ds_read_b64_tr_b16 v[136:137], v193 offset:27136
	v_exp_f32_e32 v225, v141
	ds_read_b128 v[180:183], v194 offset:2560
	v_add_f32_e32 v138, v223, v215
	v_mfma_f32_32x32x16_bf16 v[34:49], v[168:171], v[216:219], v[34:49]
	v_add_f32_e32 v138, v229, v138
	v_add_f32_e32 v138, v224, v138
	v_add_f32_e32 v215, v225, v138
	v_cvt_pk_bf16_f32 v164, v164, v165
	v_cvt_pk_bf16_f32 v165, v195, v213
	v_exp_f32_e32 v195, v142
	s_waitcnt lgkmcnt(0)
	v_mfma_f32_32x32x16_bf16 v[66:81], v[180:183], v[152:155], v[66:81]
	v_exp_f32_e32 v213, v143
	v_exp_f32_e32 v180, v144
	ds_read_b64_tr_b16 v[138:139], v193 offset:30720
	ds_read_b64_tr_b16 v[140:141], v193 offset:31232
	v_exp_f32_e32 v181, v145
	ds_read_b128 v[216:219], v194 offset:4096
	v_add_f32_e32 v142, v195, v215
	v_mfma_f32_32x32x16_bf16 v[2:17], v[168:171], v[130:133], v[2:17]
	v_add_f32_e32 v142, v213, v142
	v_add_f32_e32 v142, v180, v142
	v_add_f32_e32 v182, v181, v142
	v_cvt_pk_bf16_f32 v166, v228, v220
	v_cvt_pk_bf16_f32 v167, v221, v222
	s_waitcnt lgkmcnt(0)
	v_mfma_f32_32x32x16_bf16 v[98:113], v[216:219], v[156:159], v[98:113]
	v_exp_f32_e32 v183, v114
	ds_read_b64_tr_b16 v[130:131], v193 offset:59392
	ds_read_b64_tr_b16 v[132:133], v193 offset:59904
	v_exp_f32_e32 v215, v115
	ds_read_b128 v[142:145], v194 offset:4608
	v_add_f32_e32 v114, v183, v182
	v_cvt_pk_bf16_f32 v168, v223, v229
	v_mfma_f32_32x32x16_bf16 v[18:33], v[172:175], v[134:137], v[18:33]
	v_add_f32_e32 v114, v215, v114
	v_cvt_pk_bf16_f32 v169, v224, v225
	v_mfma_f32_32x32x16_bf16 v[50:65], v[172:175], v[138:141], v[50:65]
	v_exp_f32_e32 v182, v116
	ds_read_b64_tr_b16 v[134:135], v193 offset:63488
	ds_read_b64_tr_b16 v[136:137], v193 offset:64000
	v_exp_f32_e32 v216, v117
	v_cvt_pk_bf16_f32 v170, v195, v213
	v_add_f32_e32 v114, v182, v114
	v_cvt_pk_bf16_f32 v171, v180, v181
	v_add_f32_e32 v114, v216, v114
	s_waitcnt lgkmcnt(2)
	v_mfma_f32_32x32x16_bf16 v[66:81], v[142:145], v[156:159], v[66:81]
	v_exp_f32_e32 v142, v118
	ds_read_b64_tr_b16 v[138:139], v193 offset:27648
	ds_read_b64_tr_b16 v[140:141], v193 offset:28160
	v_exp_f32_e32 v143, v119
	ds_read_b128 v[116:119], v194 offset:6144
	v_add_f32_e32 v114, v142, v114
	v_add_f32_e32 v114, v143, v114
	v_mfma_f32_32x32x16_bf16 v[34:49], v[172:175], v[130:133], v[34:49]
	s_waitcnt lgkmcnt(3)
	v_mfma_f32_32x32x16_bf16 v[2:17], v[172:175], v[134:137], v[2:17]
	v_exp_f32_e32 v144, v120
	ds_read_b64_tr_b16 v[130:131], v193 offset:31744
	ds_read_b64_tr_b16 v[132:133], v193 offset:32256
	v_exp_f32_e32 v145, v121
	v_add_f32_e32 v114, v144, v114
	v_add_f32_e32 v172, v145, v114
	s_waitcnt lgkmcnt(2)
	v_mfma_f32_32x32x16_bf16 v[98:113], v[116:119], v[160:163], v[98:113]
	v_exp_f32_e32 v114, v122
	ds_read_b64_tr_b16 v[134:135], v193 offset:60416
	ds_read_b64_tr_b16 v[136:137], v193 offset:60928
	v_exp_f32_e32 v115, v123
	ds_read_b128 v[118:121], v194 offset:6656
	v_add_f32_e32 v116, v114, v172
	v_cvt_pk_bf16_f32 v172, v183, v215
	v_mfma_f32_32x32x16_bf16 v[18:33], v[176:179], v[138:141], v[18:33]
	v_add_f32_e32 v180, v115, v116
	v_cvt_pk_bf16_f32 v173, v182, v216
	s_waitcnt lgkmcnt(3)
	v_mfma_f32_32x32x16_bf16 v[50:65], v[176:179], v[130:133], v[50:65]
	v_exp_f32_e32 v116, v124
	v_exp_f32_e32 v117, v125
	ds_read_b64_tr_b16 v[122:123], v193 offset:64512
	ds_read_b64_tr_b16 v[124:125], v193 offset:65024
	v_cvt_pk_bf16_f32 v174, v142, v143
	v_add_f32_e32 v138, v116, v180
	v_add_f32_e32 v138, v117, v138
	v_cvt_pk_bf16_f32 v175, v144, v145
	s_waitcnt lgkmcnt(2)
	v_mfma_f32_32x32x16_bf16 v[66:81], v[118:121], v[160:163], v[66:81]
	v_exp_f32_e32 v118, v126
	v_exp_f32_e32 v119, v127
	v_add_f32_e32 v120, v118, v138
	v_add_f32_e32 v126, v119, v120
	v_mfma_f32_32x32x16_bf16 v[34:49], v[176:179], v[134:137], v[34:49]
	s_waitcnt lgkmcnt(0)
	v_mfma_f32_32x32x16_bf16 v[2:17], v[176:179], v[122:125], v[2:17]
	v_exp_f32_e32 v120, v128
	v_exp_f32_e32 v121, v129
	v_add_f32_e32 v122, v120, v126
	v_add_f32_e32 v122, v121, v122
	s_andn2_b64 vcc, exec, s[4:5]
	s_cbranch_vccz .Lattn_rare_m1_b5

.Lattn_rare_m1_a1:
	v_max_f32_e32 v82, v122, v122
	v_max_f32_e32 v122, 0, v82
	v_exp_f32_e64 v123, -v122
	v_add_f32_e32 v210, v210, v122
	v_xor_b32_e32 v82, 0x80000000, v210
	v_mov_b32_e32 v83, v82
	v_mov_b32_e32 v84, v82
	v_mov_b32_e32 v85, v82
	v_mov_b32_e32 v86, v82
	v_mov_b32_e32 v87, v82
	v_mov_b32_e32 v88, v82
	v_mov_b32_e32 v89, v82
	v_mov_b32_e32 v90, v82
	v_mov_b32_e32 v91, v82
	v_mov_b32_e32 v92, v82
	v_mov_b32_e32 v93, v82
	v_mov_b32_e32 v94, v82
	v_mov_b32_e32 v95, v82
	v_mov_b32_e32 v96, v82
	v_mov_b32_e32 v97, v82
	s_and_saveexec_b64 s[82:83], s[6:7]
	ds_write_b32 v147, v123
	s_or_b64 exec, exec, s[82:83]
	v_sub_f32_e32 v113, v113, v122
	v_sub_f32_e32 v112, v112, v122
	v_sub_f32_e32 v111, v111, v122
	v_sub_f32_e32 v110, v110, v122
	v_sub_f32_e32 v109, v109, v122
	v_sub_f32_e32 v108, v108, v122
	v_sub_f32_e32 v107, v107, v122
	v_sub_f32_e32 v106, v106, v122
	v_sub_f32_e32 v105, v105, v122
	v_sub_f32_e32 v104, v104, v122
	v_sub_f32_e32 v103, v103, v122
	v_sub_f32_e32 v102, v102, v122
	v_sub_f32_e32 v101, v101, v122
	v_sub_f32_e32 v100, v100, v122
	v_sub_f32_e32 v99, v99, v122
	v_sub_f32_e32 v98, v98, v122
	v_sub_f32_e32 v81, v81, v122
	v_sub_f32_e32 v80, v80, v122
	v_sub_f32_e32 v79, v79, v122
	v_sub_f32_e32 v78, v78, v122
	v_sub_f32_e32 v77, v77, v122
	v_sub_f32_e32 v76, v76, v122
	v_sub_f32_e32 v75, v75, v122
	v_sub_f32_e32 v74, v74, v122
	v_sub_f32_e32 v73, v73, v122
	v_sub_f32_e32 v72, v72, v122
	v_sub_f32_e32 v71, v71, v122
	v_sub_f32_e32 v70, v70, v122
	v_sub_f32_e32 v69, v69, v122
	v_sub_f32_e32 v68, v68, v122
	v_sub_f32_e32 v67, v67, v122
	v_sub_f32_e32 v66, v66, v122
	v_mul_f32_e32 v213, v213, v123
	s_branch .LBB0_861
.Lattn_rare_m1_b2:
	s_waitcnt lgkmcnt(0)
	ds_read_b128 v[68:71], v214 offset:96
	ds_read_b128 v[98:101], v214 offset:64
	ds_read_b128 v[102:105], v214 offset:32
	ds_read_b128 v[106:109], v214
	s_waitcnt lgkmcnt(0)
	s_waitcnt lgkmcnt(3)
	v_pk_mul_f32 v[30:31], v[30:31], v[68:69]
	s_waitcnt lgkmcnt(2)
	v_pk_mul_f32 v[26:27], v[26:27], v[98:99]
	s_waitcnt lgkmcnt(1)
	v_pk_mul_f32 v[22:23], v[22:23], v[102:103]
	v_pk_mul_f32 v[32:33], v[32:33], v[70:71]
	v_pk_mul_f32 v[28:29], v[28:29], v[100:101]
	v_pk_mul_f32 v[24:25], v[24:25], v[104:105]
	s_waitcnt lgkmcnt(0)
	v_pk_mul_f32 v[20:21], v[20:21], v[108:109]
	v_pk_mul_f32 v[18:19], v[18:19], v[106:107]
	v_pk_mul_f32 v[62:63], v[62:63], v[68:69]
	v_pk_mul_f32 v[58:59], v[58:59], v[98:99]
	v_pk_mul_f32 v[54:55], v[54:55], v[102:103]
	v_pk_mul_f32 v[64:65], v[64:65], v[70:71]
	v_pk_mul_f32 v[60:61], v[60:61], v[100:101]
	v_pk_mul_f32 v[56:57], v[56:57], v[104:105]
	v_pk_mul_f32 v[52:53], v[52:53], v[108:109]
	v_pk_mul_f32 v[50:51], v[50:51], v[106:107]
	v_pk_mul_f32 v[46:47], v[46:47], v[68:69]
	v_pk_mul_f32 v[42:43], v[42:43], v[98:99]
	v_pk_mul_f32 v[38:39], v[38:39], v[102:103]
	v_pk_mul_f32 v[48:49], v[48:49], v[70:71]
	v_pk_mul_f32 v[44:45], v[44:45], v[100:101]
	v_pk_mul_f32 v[40:41], v[40:41], v[104:105]
	v_pk_mul_f32 v[36:37], v[36:37], v[108:109]
	v_pk_mul_f32 v[34:35], v[34:35], v[106:107]
	v_pk_mul_f32 v[14:15], v[14:15], v[68:69]
	v_pk_mul_f32 v[10:11], v[10:11], v[98:99]
	v_pk_mul_f32 v[6:7], v[6:7], v[102:103]
	v_pk_mul_f32 v[16:17], v[16:17], v[70:71]
	v_pk_mul_f32 v[12:13], v[12:13], v[100:101]
	v_pk_mul_f32 v[8:9], v[8:9], v[104:105]
	v_pk_mul_f32 v[4:5], v[4:5], v[108:109]
	v_pk_mul_f32 v[2:3], v[2:3], v[106:107]
	s_branch .LBB0_863
.Lattn_rare_m1_c3:
	v_add_u32_e32 v67, 32, v185
	v_cmp_le_i32_e32 vcc, v67, v212
	v_add_u32_e32 v67, 33, v185
	s_nop 0
	v_cndmask_b32_e32 v114, v206, v114, vcc
	v_cmp_lt_i32_e32 vcc, v185, v212
	s_nop 1
	v_cndmask_b32_e32 v131, v206, v131, vcc
	v_cmp_le_i32_e32 vcc, v185, v212
	s_nop 1
	v_cndmask_b32_e32 v130, v206, v130, vcc
	v_cmp_le_i32_e32 vcc, v67, v212
	v_add_u32_e32 v67, 2, v185
	s_nop 0
	v_cndmask_b32_e32 v115, v206, v115, vcc
	v_cmp_le_i32_e32 vcc, v67, v212
	v_add_u32_e32 v67, 34, v185
	s_nop 0
	v_cndmask_b32_e32 v132, v206, v132, vcc
	v_cmp_le_i32_e32 vcc, v67, v212
	v_add_u32_e32 v67, 3, v185
	s_nop 0
	v_cndmask_b32_e32 v116, v206, v116, vcc
	v_cmp_le_i32_e32 vcc, v67, v212
	v_add_u32_e32 v67, 35, v185
	s_nop 0
	v_cndmask_b32_e32 v133, v206, v133, vcc
	v_cmp_le_i32_e32 vcc, v67, v212
	v_add_u32_e32 v67, 8, v185
	s_nop 0
	v_cndmask_b32_e32 v117, v206, v117, vcc
	v_cmp_le_i32_e32 vcc, v67, v212
	v_add_u32_e32 v67, 40, v185
	s_nop 0
	v_cndmask_b32_e32 v134, v206, v134, vcc
	v_cmp_le_i32_e32 vcc, v67, v212
	v_add_u32_e32 v67, 9, v185
	s_nop 0
	v_cndmask_b32_e32 v118, v206, v118, vcc
	v_cmp_le_i32_e32 vcc, v67, v212
	v_add_u32_e32 v67, 41, v185
	s_nop 0
	v_cndmask_b32_e32 v135, v206, v135, vcc
	v_cmp_le_i32_e32 vcc, v67, v212
	v_add_u32_e32 v67, 10, v185
	s_nop 0
	v_cndmask_b32_e32 v119, v206, v119, vcc
	v_cmp_le_i32_e32 vcc, v67, v212
	v_add_u32_e32 v67, 42, v185
	s_nop 0
	v_cndmask_b32_e32 v136, v206, v136, vcc
	v_cmp_le_i32_e32 vcc, v67, v212
	v_add_u32_e32 v67, 11, v185
	s_nop 0
	v_cndmask_b32_e32 v120, v206, v120, vcc
	v_cmp_le_i32_e32 vcc, v67, v212
	v_add_u32_e32 v67, 43, v185
	s_nop 0
	v_cndmask_b32_e32 v137, v206, v137, vcc
	v_cmp_le_i32_e32 vcc, v67, v212
	v_add_u32_e32 v67, 16, v185
	s_nop 0
	v_cndmask_b32_e32 v121, v206, v121, vcc
	v_cmp_le_i32_e32 vcc, v67, v212
	v_add_u32_e32 v67, 48, v185
	s_nop 0
	v_cndmask_b32_e32 v138, v206, v138, vcc
	v_cmp_le_i32_e32 vcc, v67, v212
	v_add_u32_e32 v67, 17, v185
	s_nop 0
	v_cndmask_b32_e32 v122, v206, v122, vcc
	v_cmp_le_i32_e32 vcc, v67, v212
	v_add_u32_e32 v67, 49, v185
	s_nop 0
	v_cndmask_b32_e32 v139, v206, v139, vcc
	v_cmp_le_i32_e32 vcc, v67, v212
	v_add_u32_e32 v67, 18, v185
	s_nop 0
	v_cndmask_b32_e32 v123, v206, v123, vcc
	v_cmp_le_i32_e32 vcc, v67, v212
	v_add_u32_e32 v67, 50, v185
	s_nop 0
	v_cndmask_b32_e32 v140, v206, v140, vcc
	v_cmp_le_i32_e32 vcc, v67, v212
	v_add_u32_e32 v67, 19, v185
	s_nop 0
	v_cndmask_b32_e32 v124, v206, v124, vcc
	v_cmp_le_i32_e32 vcc, v67, v212
	v_add_u32_e32 v67, 51, v185
	s_nop 0
	v_cndmask_b32_e32 v141, v206, v141, vcc
	v_cmp_le_i32_e32 vcc, v67, v212
	v_add_u32_e32 v67, 24, v185
	s_nop 0
	v_cndmask_b32_e32 v125, v206, v125, vcc
	v_cmp_le_i32_e32 vcc, v67, v212
	v_add_u32_e32 v67, 56, v185
	s_nop 0
	v_cndmask_b32_e32 v142, v206, v142, vcc
	v_cmp_le_i32_e32 vcc, v67, v212
	v_add_u32_e32 v67, 25, v185
	s_nop 0
	v_cndmask_b32_e32 v126, v206, v126, vcc
	v_cmp_le_i32_e32 vcc, v67, v212
	v_add_u32_e32 v67, 57, v185
	s_nop 0
	v_cndmask_b32_e32 v143, v206, v143, vcc
	v_cmp_le_i32_e32 vcc, v67, v212
	v_add_u32_e32 v67, 26, v185
	s_nop 0
	v_cndmask_b32_e32 v127, v206, v127, vcc
	v_cmp_le_i32_e32 vcc, v67, v212
	v_add_u32_e32 v67, 58, v185
	s_nop 0
	v_cndmask_b32_e32 v144, v206, v144, vcc
	v_cmp_le_i32_e32 vcc, v67, v212
	v_add_u32_e32 v67, 27, v185
	s_nop 0
	v_cndmask_b32_e32 v128, v206, v128, vcc
	v_cmp_le_i32_e32 vcc, v67, v212
	v_add_u32_e32 v67, 59, v185
	s_nop 0
	v_cndmask_b32_e32 v145, v206, v145, vcc
	v_cmp_le_i32_e32 vcc, v67, v212
	s_nop 1
	v_cndmask_b32_e32 v129, v206, v129, vcc
	s_branch .LBB0_865
.Lattn_rare_m1_a4:
	v_max_f32_e32 v82, v98, v98
	v_max_f32_e32 v98, 0, v82
	v_exp_f32_e64 v99, -v98
	v_add_f32_e32 v210, v210, v98
	v_xor_b32_e32 v82, 0x80000000, v210
	v_mov_b32_e32 v83, v82
	v_mov_b32_e32 v84, v82
	v_mov_b32_e32 v85, v82
	v_mov_b32_e32 v86, v82
	v_mov_b32_e32 v87, v82
	v_mov_b32_e32 v88, v82
	v_mov_b32_e32 v89, v82
	v_mov_b32_e32 v90, v82
	v_mov_b32_e32 v91, v82
	v_mov_b32_e32 v92, v82
	v_mov_b32_e32 v93, v82
	v_mov_b32_e32 v94, v82
	v_mov_b32_e32 v95, v82
	v_mov_b32_e32 v96, v82
	v_mov_b32_e32 v97, v82
	s_and_saveexec_b64 s[22:23], s[6:7]
	ds_write_b32 v147, v99
	s_or_b64 exec, exec, s[22:23]
	v_sub_f32_e32 v145, v145, v98
	v_sub_f32_e32 v144, v144, v98
	v_sub_f32_e32 v143, v143, v98
	v_sub_f32_e32 v142, v142, v98
	v_sub_f32_e32 v141, v141, v98
	v_sub_f32_e32 v140, v140, v98
	v_sub_f32_e32 v139, v139, v98
	v_sub_f32_e32 v138, v138, v98
	v_sub_f32_e32 v137, v137, v98
	v_sub_f32_e32 v136, v136, v98
	v_sub_f32_e32 v135, v135, v98
	v_sub_f32_e32 v134, v134, v98
	v_sub_f32_e32 v133, v133, v98
	v_sub_f32_e32 v132, v132, v98
	v_sub_f32_e32 v131, v131, v98
	v_sub_f32_e32 v130, v130, v98
	v_sub_f32_e32 v129, v129, v98
	v_sub_f32_e32 v128, v128, v98
	v_sub_f32_e32 v127, v127, v98
	v_sub_f32_e32 v126, v126, v98
	v_sub_f32_e32 v125, v125, v98
	v_sub_f32_e32 v124, v124, v98
	v_sub_f32_e32 v123, v123, v98
	v_sub_f32_e32 v122, v122, v98
	v_sub_f32_e32 v121, v121, v98
	v_sub_f32_e32 v120, v120, v98
	v_sub_f32_e32 v119, v119, v98
	v_sub_f32_e32 v118, v118, v98
	v_sub_f32_e32 v117, v117, v98
	v_sub_f32_e32 v116, v116, v98
	v_sub_f32_e32 v115, v115, v98
	v_sub_f32_e32 v114, v114, v98
	v_mul_f32_e32 v192, v192, v99
	s_branch .LBB0_874
.Lattn_rare_m1_b5:
	s_waitcnt lgkmcnt(0)
	ds_read_b128 v[124:127], v214 offset:96
	ds_read_b128 v[128:131], v214 offset:64
	ds_read_b128 v[132:135], v214
	ds_read_b128 v[136:139], v214 offset:32
	s_waitcnt lgkmcnt(0)
	s_waitcnt lgkmcnt(3)
	v_pk_mul_f32 v[32:33], v[32:33], v[126:127]
	v_pk_mul_f32 v[30:31], v[30:31], v[124:125]
	s_waitcnt lgkmcnt(2)
	v_pk_mul_f32 v[28:29], v[28:29], v[130:131]
	v_pk_mul_f32 v[26:27], v[26:27], v[128:129]
	s_waitcnt lgkmcnt(0)
	v_pk_mul_f32 v[24:25], v[24:25], v[138:139]
	v_pk_mul_f32 v[22:23], v[22:23], v[136:137]
	v_pk_mul_f32 v[20:21], v[20:21], v[134:135]
	v_pk_mul_f32 v[18:19], v[18:19], v[132:133]
	v_pk_mul_f32 v[64:65], v[64:65], v[126:127]
	v_pk_mul_f32 v[62:63], v[62:63], v[124:125]
	v_pk_mul_f32 v[60:61], v[60:61], v[130:131]
	v_pk_mul_f32 v[58:59], v[58:59], v[128:129]
	v_pk_mul_f32 v[56:57], v[56:57], v[138:139]
	v_pk_mul_f32 v[54:55], v[54:55], v[136:137]
	v_pk_mul_f32 v[52:53], v[52:53], v[134:135]
	v_pk_mul_f32 v[50:51], v[50:51], v[132:133]
	v_pk_mul_f32 v[48:49], v[48:49], v[126:127]
	v_pk_mul_f32 v[46:47], v[46:47], v[124:125]
	v_pk_mul_f32 v[44:45], v[44:45], v[130:131]
	v_pk_mul_f32 v[42:43], v[42:43], v[128:129]
	v_pk_mul_f32 v[40:41], v[40:41], v[138:139]
	v_pk_mul_f32 v[38:39], v[38:39], v[136:137]
	v_pk_mul_f32 v[36:37], v[36:37], v[134:135]
	v_pk_mul_f32 v[34:35], v[34:35], v[132:133]
	v_pk_mul_f32 v[16:17], v[16:17], v[126:127]
	v_pk_mul_f32 v[14:15], v[14:15], v[124:125]
	v_pk_mul_f32 v[12:13], v[12:13], v[130:131]
	v_pk_mul_f32 v[10:11], v[10:11], v[128:129]
	v_pk_mul_f32 v[8:9], v[8:9], v[138:139]
	v_pk_mul_f32 v[6:7], v[6:7], v[136:137]
	v_pk_mul_f32 v[4:5], v[4:5], v[134:135]
	v_pk_mul_f32 v[2:3], v[2:3], v[132:133]
	s_branch .LBB0_876
.Lattn_rare_m1_c6:
	v_add_u32_e32 v124, 0x60, v185
	v_add_u32_e32 v123, 64, v185
	v_cmp_le_i32_e32 vcc, v124, v212
	s_nop 1
	v_cndmask_b32_e32 v66, v206, v66, vcc
	v_cmp_lt_i32_e32 vcc, v123, v212
	s_nop 1
	v_cndmask_b32_e32 v99, v206, v99, vcc
	v_cmp_le_i32_e32 vcc, v123, v212
	v_add_u32_e32 v123, 0x61, v185
	s_nop 0
	v_cndmask_b32_e32 v98, v206, v98, vcc
	v_cmp_le_i32_e32 vcc, v123, v212
	v_add_u32_e32 v123, 0x42, v185
	s_nop 0
	v_cndmask_b32_e32 v67, v206, v67, vcc
	v_cmp_le_i32_e32 vcc, v123, v212
	v_add_u32_e32 v123, 0x62, v185
	s_nop 0
	v_cndmask_b32_e32 v100, v206, v100, vcc
	v_cmp_le_i32_e32 vcc, v123, v212
	v_add_u32_e32 v123, 0x43, v185
	s_nop 0
	v_cndmask_b32_e32 v68, v206, v68, vcc
	v_cmp_le_i32_e32 vcc, v123, v212
	v_add_u32_e32 v123, 0x63, v185
	s_nop 0
	v_cndmask_b32_e32 v101, v206, v101, vcc
	v_cmp_le_i32_e32 vcc, v123, v212
	v_add_u32_e32 v123, 0x48, v185
	s_nop 0
	v_cndmask_b32_e32 v69, v206, v69, vcc
	v_cmp_le_i32_e32 vcc, v123, v212
	v_add_u32_e32 v123, 0x68, v185
	s_nop 0
	v_cndmask_b32_e32 v102, v206, v102, vcc
	v_cmp_le_i32_e32 vcc, v123, v212
	v_add_u32_e32 v123, 0x49, v185
	s_nop 0
	v_cndmask_b32_e32 v70, v206, v70, vcc
	v_cmp_le_i32_e32 vcc, v123, v212
	v_add_u32_e32 v123, 0x69, v185
	s_nop 0
	v_cndmask_b32_e32 v103, v206, v103, vcc
	v_cmp_le_i32_e32 vcc, v123, v212
	v_add_u32_e32 v123, 0x4a, v185
	s_nop 0
	v_cndmask_b32_e32 v71, v206, v71, vcc
	v_cmp_le_i32_e32 vcc, v123, v212
	v_add_u32_e32 v123, 0x6a, v185
	s_nop 0
	v_cndmask_b32_e32 v104, v206, v104, vcc
	v_cmp_le_i32_e32 vcc, v123, v212
	v_add_u32_e32 v123, 0x4b, v185
	s_nop 0
	v_cndmask_b32_e32 v72, v206, v72, vcc
	v_cmp_le_i32_e32 vcc, v123, v212
	v_add_u32_e32 v123, 0x6b, v185
	s_nop 0
	v_cndmask_b32_e32 v105, v206, v105, vcc
	v_cmp_le_i32_e32 vcc, v123, v212
	v_add_u32_e32 v123, 0x50, v185
	s_nop 0
	v_cndmask_b32_e32 v73, v206, v73, vcc
	v_cmp_le_i32_e32 vcc, v123, v212
	v_add_u32_e32 v123, 0x70, v185
	s_nop 0
	v_cndmask_b32_e32 v106, v206, v106, vcc
	v_cmp_le_i32_e32 vcc, v123, v212
	v_add_u32_e32 v123, 0x51, v185
	s_nop 0
	v_cndmask_b32_e32 v74, v206, v74, vcc
	v_cmp_le_i32_e32 vcc, v123, v212
	v_add_u32_e32 v123, 0x71, v185
	s_nop 0
	v_cndmask_b32_e32 v107, v206, v107, vcc
	v_cmp_le_i32_e32 vcc, v123, v212
	v_add_u32_e32 v123, 0x52, v185
	s_nop 0
	v_cndmask_b32_e32 v75, v206, v75, vcc
	v_cmp_le_i32_e32 vcc, v123, v212
	v_add_u32_e32 v123, 0x72, v185
	s_nop 0
	v_cndmask_b32_e32 v108, v206, v108, vcc
	v_cmp_le_i32_e32 vcc, v123, v212
	v_add_u32_e32 v123, 0x53, v185
	s_nop 0
	v_cndmask_b32_e32 v76, v206, v76, vcc
	v_cmp_le_i32_e32 vcc, v123, v212
	v_add_u32_e32 v123, 0x73, v185
	s_nop 0
	v_cndmask_b32_e32 v109, v206, v109, vcc
	v_cmp_le_i32_e32 vcc, v123, v212
	v_add_u32_e32 v123, 0x58, v185
	s_nop 0
	v_cndmask_b32_e32 v77, v206, v77, vcc
	v_cmp_le_i32_e32 vcc, v123, v212
	v_add_u32_e32 v123, 0x78, v185
	s_nop 0
	v_cndmask_b32_e32 v110, v206, v110, vcc
	v_cmp_le_i32_e32 vcc, v123, v212
	v_add_u32_e32 v123, 0x59, v185
	s_nop 0
	v_cndmask_b32_e32 v78, v206, v78, vcc
	v_cmp_le_i32_e32 vcc, v123, v212
	v_add_u32_e32 v123, 0x79, v185
	s_nop 0
	v_cndmask_b32_e32 v111, v206, v111, vcc
	v_cmp_le_i32_e32 vcc, v123, v212
	v_add_u32_e32 v123, 0x5a, v185
	s_nop 0
	v_cndmask_b32_e32 v79, v206, v79, vcc
	v_cmp_le_i32_e32 vcc, v123, v212
	v_add_u32_e32 v123, 0x7a, v185
	s_nop 0
	v_cndmask_b32_e32 v112, v206, v112, vcc
	v_cmp_le_i32_e32 vcc, v123, v212
	v_add_u32_e32 v123, 0x5b, v185
	s_nop 0
	v_cndmask_b32_e32 v80, v206, v80, vcc
	v_cmp_le_i32_e32 vcc, v123, v212
	v_add_u32_e32 v123, 0x7b, v185
	s_nop 0
	v_cndmask_b32_e32 v113, v206, v113, vcc
	v_cmp_le_i32_e32 vcc, v123, v212
	s_nop 1
	v_cndmask_b32_e32 v81, v206, v81, vcc
	s_branch .LBB0_878

.LBB0_886:
	s_mulk_i32 s50, 0x6000
	s_sub_i32 s4, s25, s50
	s_add_i32 s4, s14, s4
	s_addk_i32 s4, 0xc000
	v_lshl_add_u64 v[68:69], v[192:193], 0, s[44:45]
	s_mov_b32 m0, s4
	s_nop 0
	global_load_lds_dwordx4 v[68:69], off
	s_andn2_b64 vcc, exec, s[76:77]
	s_cbranch_vccz .LBB0_869
	s_branch .LBB0_870

.LBB0_891:
	s_mov_b64 s[6:7], s[0:1]
	s_waitcnt vmcnt(0) lgkmcnt(0)
	s_barrier
	s_load_dwordx2 s[6:7], s[6:7], 0xa0
	s_ashr_i32 s14, s13, 31
	s_add_u32 s22, s61, s13
	s_addc_u32 s23, s63, s14
	s_lshl_b64 s[22:23], s[22:23], 11
	s_waitcnt lgkmcnt(0)
	s_add_u32 s5, s6, s22
	s_addc_u32 s7, s7, s23
	s_add_u32 s6, s5, s64
	v_and_b32_e32 v83, 56, v211
	s_addc_u32 s7, s7, s65
	v_lshlrev_b32_e32 v188, 1, v83
	v_mov_b32_e32 v189, v146
	v_lshl_add_u64 v[84:85], s[6:7], 0, v[188:189]
	v_lshlrev_b32_e32 v83, 8, v1
	v_lshl_add_u64 v[86:87], v[84:85], 0, s[86:87]
	v_and_b32_e32 v88, 0x3800, v83
	v_mov_b32_e32 v89, v146
	v_lshl_add_u64 v[90:91], v[86:87], 0, v[88:89]
	v_or_b32_e32 v92, 0x4000, v88
	v_mov_b32_e32 v93, v146
	v_or_b32_e32 v96, 0x8000, v88
	v_mov_b32_e32 v97, v146
	v_or_b32_e32 v88, 0xc000, v88
	s_mov_b64 s[6:7], 0x14800080
	v_lshl_add_u64 v[94:95], v[86:87], 0, v[92:93]
	v_lshl_add_u64 v[114:115], v[86:87], 0, v[96:97]
	v_lshl_add_u64 v[86:87], v[86:87], 0, v[88:89]
	v_lshl_add_u64 v[84:85], v[84:85], 0, s[6:7]
	global_load_dwordx4 v[130:133], v[94:95], off
	global_load_dwordx4 v[134:137], v[114:115], off
	global_load_dwordx4 v[138:141], v[90:91], off
	s_nop 0
	global_load_dwordx4 v[114:117], v[90:91], off offset:128
	v_lshl_add_u64 v[90:91], v[84:85], 0, v[92:93]
	global_load_dwordx4 v[142:145], v[86:87], off
	global_load_dwordx4 v[118:121], v[90:91], off
	v_lshl_add_u64 v[86:87], v[84:85], 0, v[96:97]
	v_lshl_add_u64 v[84:85], v[84:85], 0, v[88:89]
	global_load_dwordx4 v[122:125], v[86:87], off
	global_load_dwordx4 v[126:129], v[84:85], off
	v_lshlrev_b32_e32 v82, 10, v1
	s_andn2_b64 vcc, exec, s[66:67]
	s_cbranch_vccnz .LBB0_893
	s_mov_b64 s[6:7], s[0:1]
	s_load_dwordx2 s[6:7], s[6:7], 0xa0
	s_lshl_b64 s[22:23], s[72:73], 13
	s_lshl_b64 s[28:29], s[72:73], 24
	s_lshl_b32 s5, s70, 1
	v_lshlrev_b32_e32 v82, 1, v82
	s_waitcnt lgkmcnt(0)
	s_add_u32 s28, s6, s28
	s_addc_u32 s29, s7, s29
	s_add_u32 s28, s28, s5
	v_mov_b32_e32 v83, v146
	s_addc_u32 s29, s29, 0
	v_lshl_add_u64 v[82:83], s[28:29], 0, v[82:83]
	v_lshl_add_u64 v[82:83], s[8:9], 1, v[82:83]
	s_add_u32 s8, s68, s22
	s_addc_u32 s9, s69, s23
	s_add_u32 s8, s8, s13
	s_addc_u32 s9, s9, s14
	v_mov_b32_e32 v187, v146
	s_lshl_b64 s[8:9], s[8:9], 11
	v_lshl_add_u64 v[86:87], s[28:29], 0, v[186:187]
	s_add_u32 s6, s6, s8
	v_lshl_add_u64 v[86:87], s[78:79], 1, v[86:87]
	v_mov_b32_e32 v185, v146
	s_addc_u32 s7, s7, s9
	v_lshl_add_u64 v[84:85], v[82:83], 0, s[16:17]
	v_lshl_add_u64 v[86:87], v[86:87], 0, v[184:185]
	s_add_u32 s6, s6, s5
	s_mov_b32 m0, s25
	s_nop 0
	global_load_lds_dwordx4 v[84:85], off
	v_lshl_add_u64 v[88:89], v[86:87], 0, s[58:59]
	s_addc_u32 s7, s7, 0
	s_mov_b32 m0, s55
	s_nop 0
	global_load_lds_dwordx4 v[88:89], off
	s_mov_b64 s[8:9], 0xc800080
	v_lshl_add_u64 v[84:85], v[86:87], 0, s[8:9]
	s_mov_b32 m0, s54
	s_nop 0
	global_load_lds_dwordx4 v[84:85], off
	s_cmp_lg_u32 0, -1
	s_cselect_b32 s5, 0, 0
	s_mov_b64 s[8:9], 0x8820000
	s_add_i32 s5, s5, s24
	v_lshl_add_u64 v[84:85], v[82:83], 0, s[8:9]
	s_add_i32 s8, s5, 0x2000
	s_mov_b32 m0, s8
	s_nop 0
	global_load_lds_dwordx4 v[84:85], off
	s_mov_b64 s[8:9], 0xc820000
	v_lshl_add_u64 v[84:85], v[86:87], 0, s[8:9]
	s_add_i32 s8, s5, 0x8000
	s_mov_b32 m0, s8
	s_nop 0
	global_load_lds_dwordx4 v[84:85], off
	s_mov_b64 s[8:9], 0xc820080
	v_lshl_add_u64 v[84:85], v[86:87], 0, s[8:9]
	s_add_i32 s8, s5, 0x10000
	s_mov_b32 m0, s8
	s_nop 0
	global_load_lds_dwordx4 v[84:85], off
	s_mov_b64 s[8:9], 0x8840000
	v_lshl_add_u64 v[82:83], v[82:83], 0, s[8:9]
	s_addk_i32 s5, 0x4000
	s_mov_b32 m0, s5
	s_nop 0
	global_load_lds_dwordx4 v[82:83], off
	v_lshlrev_b32_e32 v82, 11, v207
	v_lshl_or_b32 v82, v208, 4, v82
	v_mov_b32_e32 v83, v146
	v_lshl_add_u64 v[82:83], s[6:7], 0, v[82:83]
	v_lshl_add_u64 v[84:85], v[82:83], 0, s[30:31]
	v_add_co_u32_e32 v82, vcc, s97, v82
	s_nop 1
	v_addc_co_u32_e32 v83, vcc, 0, v83, vcc
	global_load_dwordx4 v[152:155], v[84:85], off offset:32
	global_load_dwordx4 v[156:159], v[84:85], off offset:64
	global_load_dwordx4 v[148:151], v[82:83], off
	global_load_dwordx4 v[160:163], v[84:85], off offset:96
